# K-loop LDS-DMA loads in saddr form (SGPR base + 32-bit offset), 86 sites; plus sc1 epilogue stores
# speedup vs baseline: 1.0650x; 1.0650x over previous
.LBB0_108:
	s_add_u32 s0, s40, 0xfffc0080
	s_addc_u32 s1, s41, -1
	s_add_i32 s68, 0, 0x10000
	s_cmp_eq_u32 s47, 12
	s_cselect_b32 s5, s6, s1
	s_cselect_b32 s4, s7, s0
	s_cselect_b32 s1, s37, s46
	s_cselect_b32 s0, s42, s43
	s_add_i32 s70, 0, 0x14000
	v_add_u32_e32 v60, s68, v250
	v_add_u32_e32 v124, s70, v250
	ds_read_b128 v[40:43], v60
	ds_read_b128 v[44:47], v60 offset:1024
	ds_read_b128 v[56:59], v60 offset:2048
	ds_read_b128 v[60:63], v60 offset:3072
	ds_read_b128 v[104:107], v124
	ds_read_b128 v[112:115], v124 offset:1024
	ds_read_b128 v[120:123], v124 offset:2048
	ds_read_b128 v[124:127], v124 offset:3072
	s_add_i32 m0, s20, 0xc000
	ds_read_b128 v[152:155], v251
	ds_read_b128 v[156:159], v251 offset:1024
	ds_read_b128 v[168:171], v251 offset:2048
	ds_read_b128 v[172:175], v251 offset:3072
	ds_read_b128 v[200:203], v251 offset:4096
	ds_read_b128 v[204:207], v251 offset:5120
	ds_read_b128 v[208:211], v251 offset:6144
	ds_read_b128 v[212:215], v251 offset:7168
	global_load_lds_dwordx4 v196, s[40:41]
	s_add_i32 m0, s20, 0xe000
	s_nop 0
	global_load_lds_dwordx4 v198, s[40:41]
	s_waitcnt vmcnt(8)
	s_waitcnt lgkmcnt(0)
	s_barrier
	s_setprio 1
	s_waitcnt lgkmcnt(0)
	v_mfma_f32_16x16x32_bf16 v[164:167], v[40:43], v[152:155], v[164:167]
	v_mfma_f32_16x16x32_bf16 v[160:163], v[56:59], v[152:155], v[160:163]
	v_mfma_f32_16x16x32_bf16 v[116:119], v[40:43], v[168:171], v[116:119]
	v_mfma_f32_16x16x32_bf16 v[108:111], v[56:59], v[168:171], v[108:111]
	v_mfma_f32_16x16x32_bf16 v[140:143], v[40:43], v[200:203], v[140:143]
	v_mfma_f32_16x16x32_bf16 v[136:139], v[56:59], v[200:203], v[136:139]
	v_mfma_f32_16x16x32_bf16 v[92:95], v[40:43], v[208:211], v[92:95]
	v_mfma_f32_16x16x32_bf16 v[88:91], v[56:59], v[208:211], v[88:91]
	v_mfma_f32_16x16x32_bf16 v[164:167], v[44:47], v[156:159], v[164:167]
	v_mfma_f32_16x16x32_bf16 v[160:163], v[60:63], v[156:159], v[160:163]
	v_mfma_f32_16x16x32_bf16 v[116:119], v[44:47], v[172:175], v[116:119]
	v_mfma_f32_16x16x32_bf16 v[108:111], v[60:63], v[172:175], v[108:111]
	v_mfma_f32_16x16x32_bf16 v[140:143], v[44:47], v[204:207], v[140:143]
	v_mfma_f32_16x16x32_bf16 v[136:139], v[60:63], v[204:207], v[136:139]
	v_mfma_f32_16x16x32_bf16 v[92:95], v[44:47], v[212:215], v[92:95]
	v_mfma_f32_16x16x32_bf16 v[88:91], v[60:63], v[212:215], v[88:91]
	s_setprio 0
	s_setprio 1
	v_mfma_f32_16x16x32_bf16 v[148:151], v[104:107], v[152:155], v[148:151]
	v_mfma_f32_16x16x32_bf16 v[144:147], v[120:123], v[152:155], v[144:147]
	v_mfma_f32_16x16x32_bf16 v[100:103], v[104:107], v[168:171], v[100:103]
	v_mfma_f32_16x16x32_bf16 v[96:99], v[120:123], v[168:171], v[96:99]
	v_mfma_f32_16x16x32_bf16 v[132:135], v[104:107], v[200:203], v[132:135]
	v_mfma_f32_16x16x32_bf16 v[128:131], v[120:123], v[200:203], v[128:131]
	v_mfma_f32_16x16x32_bf16 v[84:87], v[104:107], v[208:211], v[84:87]
	v_mfma_f32_16x16x32_bf16 v[80:83], v[120:123], v[208:211], v[80:83]
	v_mfma_f32_16x16x32_bf16 v[148:151], v[112:115], v[156:159], v[148:151]
	v_mfma_f32_16x16x32_bf16 v[144:147], v[124:127], v[156:159], v[144:147]
	v_mfma_f32_16x16x32_bf16 v[100:103], v[112:115], v[172:175], v[100:103]
	v_mfma_f32_16x16x32_bf16 v[96:99], v[124:127], v[172:175], v[96:99]
	v_mfma_f32_16x16x32_bf16 v[132:135], v[112:115], v[204:207], v[132:135]
	v_mfma_f32_16x16x32_bf16 v[128:131], v[124:127], v[204:207], v[128:131]
	v_mfma_f32_16x16x32_bf16 v[84:87], v[112:115], v[212:215], v[84:87]
	v_mfma_f32_16x16x32_bf16 v[80:83], v[124:127], v[212:215], v[80:83]
	s_setprio 0
	s_barrier
	s_add_i32 s68, s68, s27
	v_lshl_add_u64 v[178:179], s[0:1], 0, v[176:177]
	s_mov_b32 m0, s68
	ds_read_b128 v[152:155], v251 offset:16384
	ds_read_b128 v[156:159], v251 offset:17408
	ds_read_b128 v[168:171], v251 offset:18432
	ds_read_b128 v[172:175], v251 offset:19456
	ds_read_b128 v[200:203], v251 offset:20480
	ds_read_b128 v[204:207], v251 offset:21504
	ds_read_b128 v[208:211], v251 offset:22528
	ds_read_b128 v[212:215], v251 offset:23552
	global_load_lds_dwordx4 v176, s[0:1]
	s_add_i32 m0, s68, 0x2000
	s_add_u32 s68, s0, 0x40000
	v_lshl_add_u64 v[180:181], s[0:1], 0, v[190:191]
	s_addc_u32 s69, s1, 0
	s_add_i32 s70, s70, s27
	global_load_lds_dwordx4 v190, s[0:1]
	s_mov_b32 m0, s70
	v_lshl_add_u64 v[188:189], s[4:5], 0, v[192:193]
	global_load_lds_dwordx4 v176, s[68:69]
	s_add_i32 m0, s70, 0x2000
	s_nop 0
	global_load_lds_dwordx4 v190, s[68:69]
	v_lshl_add_u64 v[186:187], s[4:5], 0, v[194:195]
	s_mov_b32 m0, s20
	s_nop 0
	global_load_lds_dwordx4 v194, s[4:5]
	s_mov_b32 m0, s12
	s_nop 0
	global_load_lds_dwordx4 v192, s[4:5]
	s_waitcnt vmcnt(8)
	s_waitcnt lgkmcnt(0)
	s_barrier
	s_setprio 1
	s_waitcnt lgkmcnt(0)
	v_mfma_f32_16x16x32_bf16 v[76:79], v[40:43], v[152:155], v[76:79]
	v_mfma_f32_16x16x32_bf16 v[72:75], v[56:59], v[152:155], v[72:75]
	v_mfma_f32_16x16x32_bf16 v[52:55], v[40:43], v[168:171], v[52:55]
	v_mfma_f32_16x16x32_bf16 v[48:51], v[56:59], v[168:171], v[48:51]
	v_mfma_f32_16x16x32_bf16 v[28:31], v[40:43], v[200:203], v[28:31]
	v_mfma_f32_16x16x32_bf16 v[24:27], v[56:59], v[200:203], v[24:27]
	v_mfma_f32_16x16x32_bf16 v[12:15], v[40:43], v[208:211], v[12:15]
	v_mfma_f32_16x16x32_bf16 v[8:11], v[56:59], v[208:211], v[8:11]
	v_mfma_f32_16x16x32_bf16 v[76:79], v[44:47], v[156:159], v[76:79]
	v_mfma_f32_16x16x32_bf16 v[72:75], v[60:63], v[156:159], v[72:75]
	v_mfma_f32_16x16x32_bf16 v[52:55], v[44:47], v[172:175], v[52:55]
	v_mfma_f32_16x16x32_bf16 v[48:51], v[60:63], v[172:175], v[48:51]
	v_mfma_f32_16x16x32_bf16 v[28:31], v[44:47], v[204:207], v[28:31]
	v_mfma_f32_16x16x32_bf16 v[24:27], v[60:63], v[204:207], v[24:27]
	v_mfma_f32_16x16x32_bf16 v[12:15], v[44:47], v[212:215], v[12:15]
	v_mfma_f32_16x16x32_bf16 v[8:11], v[60:63], v[212:215], v[8:11]
	s_setprio 0
	s_setprio 1
	v_mfma_f32_16x16x32_bf16 v[36:39], v[104:107], v[168:171], v[36:39]
	v_mfma_f32_16x16x32_bf16 v[32:35], v[120:123], v[168:171], v[32:35]
	v_mfma_f32_16x16x32_bf16 v[20:23], v[104:107], v[200:203], v[20:23]
	v_mfma_f32_16x16x32_bf16 v[16:19], v[120:123], v[200:203], v[16:19]
	v_mfma_f32_16x16x32_bf16 v[4:7], v[104:107], v[208:211], v[4:7]
	v_mfma_f32_16x16x32_bf16 v[0:3], v[120:123], v[208:211], v[0:3]
	v_mfma_f32_16x16x32_bf16 v[40:43], v[104:107], v[152:155], v[68:71]
	v_mfma_f32_16x16x32_bf16 v[44:47], v[120:123], v[152:155], v[64:67]
	v_mfma_f32_16x16x32_bf16 v[36:39], v[112:115], v[172:175], v[36:39]
	v_mfma_f32_16x16x32_bf16 v[32:35], v[124:127], v[172:175], v[32:35]
	v_mfma_f32_16x16x32_bf16 v[20:23], v[112:115], v[204:207], v[20:23]
	v_mfma_f32_16x16x32_bf16 v[16:19], v[124:127], v[204:207], v[16:19]
	v_mfma_f32_16x16x32_bf16 v[4:7], v[112:115], v[212:215], v[4:7]
	v_mfma_f32_16x16x32_bf16 v[0:3], v[124:127], v[212:215], v[0:3]
	v_mfma_f32_16x16x32_bf16 v[40:43], v[112:115], v[156:159], v[40:43]
	v_mfma_f32_16x16x32_bf16 v[44:47], v[124:127], v[156:159], v[44:47]
	s_setprio 0
	s_barrier
	s_add_i32 s68, 0, 0x18000
	s_add_i32 s69, 0, 0x1c000
	v_add_u32_e32 v68, s68, v250
	v_add_u32_e32 v124, s69, v250
	ds_read_b128 v[56:59], v68
	ds_read_b128 v[60:63], v68 offset:1024
	ds_read_b128 v[64:67], v68 offset:2048
	ds_read_b128 v[68:71], v68 offset:3072
	ds_read_b128 v[104:107], v124
	ds_read_b128 v[112:115], v124 offset:1024
	ds_read_b128 v[120:123], v124 offset:2048
	ds_read_b128 v[124:127], v124 offset:3072
	s_add_u32 s4, s4, 0x40000
	s_addc_u32 s5, s5, 0
	s_mov_b32 m0, s60
	ds_read_b128 v[152:155], v251 offset:32768
	ds_read_b128 v[156:159], v251 offset:33792
	ds_read_b128 v[168:171], v251 offset:34816
	ds_read_b128 v[172:175], v251 offset:35840
	ds_read_b128 v[200:203], v251 offset:36864
	ds_read_b128 v[204:207], v251 offset:37888
	ds_read_b128 v[208:211], v251 offset:38912
	ds_read_b128 v[212:215], v251 offset:39936
	global_load_lds_dwordx4 v194, s[4:5]
	s_mov_b32 m0, s61
	s_nop 0
	global_load_lds_dwordx4 v192, s[4:5]
	s_waitcnt vmcnt(8)
	s_waitcnt lgkmcnt(0)
	s_barrier
	s_setprio 1
	s_waitcnt lgkmcnt(0)
	v_mfma_f32_16x16x32_bf16 v[164:167], v[56:59], v[152:155], v[164:167]
	v_mfma_f32_16x16x32_bf16 v[160:163], v[64:67], v[152:155], v[160:163]
	v_mfma_f32_16x16x32_bf16 v[116:119], v[56:59], v[168:171], v[116:119]
	v_mfma_f32_16x16x32_bf16 v[108:111], v[64:67], v[168:171], v[108:111]
	v_mfma_f32_16x16x32_bf16 v[140:143], v[56:59], v[200:203], v[140:143]
	v_mfma_f32_16x16x32_bf16 v[136:139], v[64:67], v[200:203], v[136:139]
	v_mfma_f32_16x16x32_bf16 v[92:95], v[56:59], v[208:211], v[92:95]
	v_mfma_f32_16x16x32_bf16 v[88:91], v[64:67], v[208:211], v[88:91]
	v_mfma_f32_16x16x32_bf16 v[164:167], v[60:63], v[156:159], v[164:167]
	v_mfma_f32_16x16x32_bf16 v[160:163], v[68:71], v[156:159], v[160:163]
	v_mfma_f32_16x16x32_bf16 v[116:119], v[60:63], v[172:175], v[116:119]
	v_mfma_f32_16x16x32_bf16 v[108:111], v[68:71], v[172:175], v[108:111]
	v_mfma_f32_16x16x32_bf16 v[140:143], v[60:63], v[204:207], v[140:143]
	v_mfma_f32_16x16x32_bf16 v[136:139], v[68:71], v[204:207], v[136:139]
	v_mfma_f32_16x16x32_bf16 v[92:95], v[60:63], v[212:215], v[92:95]
	v_mfma_f32_16x16x32_bf16 v[88:91], v[68:71], v[212:215], v[88:91]
	s_setprio 0
	s_setprio 1
	v_mfma_f32_16x16x32_bf16 v[148:151], v[104:107], v[152:155], v[148:151]
	v_mfma_f32_16x16x32_bf16 v[144:147], v[120:123], v[152:155], v[144:147]
	v_mfma_f32_16x16x32_bf16 v[100:103], v[104:107], v[168:171], v[100:103]
	v_mfma_f32_16x16x32_bf16 v[96:99], v[120:123], v[168:171], v[96:99]
	v_mfma_f32_16x16x32_bf16 v[132:135], v[104:107], v[200:203], v[132:135]
	v_mfma_f32_16x16x32_bf16 v[128:131], v[120:123], v[200:203], v[128:131]
	v_mfma_f32_16x16x32_bf16 v[84:87], v[104:107], v[208:211], v[84:87]
	v_mfma_f32_16x16x32_bf16 v[80:83], v[120:123], v[208:211], v[80:83]
	v_mfma_f32_16x16x32_bf16 v[148:151], v[112:115], v[156:159], v[148:151]
	v_mfma_f32_16x16x32_bf16 v[144:147], v[124:127], v[156:159], v[144:147]
	v_mfma_f32_16x16x32_bf16 v[100:103], v[112:115], v[172:175], v[100:103]
	v_mfma_f32_16x16x32_bf16 v[96:99], v[124:127], v[172:175], v[96:99]
	v_mfma_f32_16x16x32_bf16 v[132:135], v[112:115], v[204:207], v[132:135]
	v_mfma_f32_16x16x32_bf16 v[128:131], v[124:127], v[204:207], v[128:131]
	v_mfma_f32_16x16x32_bf16 v[84:87], v[112:115], v[212:215], v[84:87]
	v_mfma_f32_16x16x32_bf16 v[80:83], v[124:127], v[212:215], v[80:83]
	s_setprio 0
	s_barrier
	s_add_i32 s4, s68, s27
	v_lshl_add_u64 v[178:179], v[178:179], 0, s[82:83]
	s_mov_b32 m0, s4
	ds_read_b128 v[152:155], v251 offset:49152
	ds_read_b128 v[156:159], v251 offset:50176
	ds_read_b128 v[168:171], v251 offset:51200
	ds_read_b128 v[172:175], v251 offset:52224
	ds_read_b128 v[200:203], v251 offset:53248
	ds_read_b128 v[204:207], v251 offset:54272
	ds_read_b128 v[208:211], v251 offset:55296
	ds_read_b128 v[212:215], v251 offset:56320
	global_load_lds_dwordx4 v[178:179], off
	s_add_i32 m0, s4, 0x2000
	s_add_u32 s0, s0, 0x40080
	v_lshl_add_u64 v[178:179], v[180:181], 0, s[82:83]
	s_addc_u32 s1, s1, 0
	s_add_i32 s4, s69, s27
	global_load_lds_dwordx4 v[178:179], off
	s_mov_b32 m0, s4
	s_nop 0
	global_load_lds_dwordx4 v176, s[0:1]
	s_add_i32 m0, s4, 0x2000
	s_nop 0
	global_load_lds_dwordx4 v190, s[0:1]
	v_lshl_add_u64 v[178:179], v[186:187], 0, s[82:83]
	s_mov_b32 m0, s64
	s_nop 0
	global_load_lds_dwordx4 v[178:179], off
	v_lshl_add_u64 v[178:179], v[188:189], 0, s[82:83]
	s_mov_b32 m0, s65
	s_nop 0
	global_load_lds_dwordx4 v[178:179], off
	s_waitcnt vmcnt(8)
	s_waitcnt lgkmcnt(0)
	s_barrier
	s_setprio 1
	s_waitcnt lgkmcnt(0)
	v_mfma_f32_16x16x32_bf16 v[76:79], v[56:59], v[152:155], v[76:79]
	v_mfma_f32_16x16x32_bf16 v[72:75], v[64:67], v[152:155], v[72:75]
	v_mfma_f32_16x16x32_bf16 v[52:55], v[56:59], v[168:171], v[52:55]
	v_mfma_f32_16x16x32_bf16 v[48:51], v[64:67], v[168:171], v[48:51]
	v_mfma_f32_16x16x32_bf16 v[28:31], v[56:59], v[200:203], v[28:31]
	v_mfma_f32_16x16x32_bf16 v[24:27], v[64:67], v[200:203], v[24:27]
	v_mfma_f32_16x16x32_bf16 v[12:15], v[56:59], v[208:211], v[12:15]
	v_mfma_f32_16x16x32_bf16 v[8:11], v[64:67], v[208:211], v[8:11]
	v_mfma_f32_16x16x32_bf16 v[76:79], v[60:63], v[156:159], v[76:79]
	v_mfma_f32_16x16x32_bf16 v[72:75], v[68:71], v[156:159], v[72:75]
	v_mfma_f32_16x16x32_bf16 v[52:55], v[60:63], v[172:175], v[52:55]
	v_mfma_f32_16x16x32_bf16 v[48:51], v[68:71], v[172:175], v[48:51]
	v_mfma_f32_16x16x32_bf16 v[28:31], v[60:63], v[204:207], v[28:31]
	v_mfma_f32_16x16x32_bf16 v[24:27], v[68:71], v[204:207], v[24:27]
	v_mfma_f32_16x16x32_bf16 v[12:15], v[60:63], v[212:215], v[12:15]
	v_mfma_f32_16x16x32_bf16 v[8:11], v[68:71], v[212:215], v[8:11]
	s_setprio 0
	s_setprio 1
	v_mfma_f32_16x16x32_bf16 v[40:43], v[104:107], v[152:155], v[40:43]
	v_mfma_f32_16x16x32_bf16 v[68:71], v[112:115], v[156:159], v[40:43]
	v_mfma_f32_16x16x32_bf16 v[40:43], v[120:123], v[152:155], v[44:47]
	v_mfma_f32_16x16x32_bf16 v[36:39], v[104:107], v[168:171], v[36:39]
	v_mfma_f32_16x16x32_bf16 v[32:35], v[120:123], v[168:171], v[32:35]
	v_mfma_f32_16x16x32_bf16 v[20:23], v[104:107], v[200:203], v[20:23]
	v_mfma_f32_16x16x32_bf16 v[16:19], v[120:123], v[200:203], v[16:19]
	v_mfma_f32_16x16x32_bf16 v[4:7], v[104:107], v[208:211], v[4:7]
	v_mfma_f32_16x16x32_bf16 v[0:3], v[120:123], v[208:211], v[0:3]
	v_mfma_f32_16x16x32_bf16 v[64:67], v[124:127], v[156:159], v[40:43]
	v_mfma_f32_16x16x32_bf16 v[36:39], v[112:115], v[172:175], v[36:39]
	v_mfma_f32_16x16x32_bf16 v[32:35], v[124:127], v[172:175], v[32:35]
	v_mfma_f32_16x16x32_bf16 v[20:23], v[112:115], v[204:207], v[20:23]
	v_mfma_f32_16x16x32_bf16 v[16:19], v[124:127], v[204:207], v[16:19]
	v_mfma_f32_16x16x32_bf16 v[4:7], v[112:115], v[212:215], v[4:7]
	v_mfma_f32_16x16x32_bf16 v[0:3], v[124:127], v[212:215], v[0:3]
	s_setprio 0
	s_barrier
	s_add_i32 s47, s47, 2
	s_add_u32 s40, s40, 0x100
	s_addc_u32 s41, s41, 0
	s_add_u32 s43, s43, 0x100
	s_addc_u32 s46, s46, 0
	s_cmp_gt_u32 s47, 13
	s_cbranch_scc0 .LBB0_108
	s_and_b64 vcc, exec, s[30:31]
	s_cbranch_vccz .LBB0_111
	s_barrier

.LBB0_571:
	s_ashr_i32 s49, s48, 31
	s_lshl_b64 s[6:7], s[48:49], 17
	s_add_u32 s50, s12, s6
	s_addc_u32 s51, s20, s7
	s_and_b64 s[6:7], s[40:41], exec
	s_cselect_b32 s57, s51, s5
	s_cselect_b32 s56, s50, s4
	s_ashr_i32 s47, s46, 31
	s_lshl_b64 s[6:7], s[46:47], 17
	s_add_u32 s52, s27, s6
	s_addc_u32 s53, s60, s7
	s_and_b64 s[6:7], s[40:41], exec
	s_cselect_b32 s55, s53, s1
	s_cselect_b32 s54, s52, s0
	s_add_i32 s72, 0, 0x10000
	s_add_i32 s47, 0, 0x14000
	v_add_u32_e32 v182, s72, v174
	v_add_u32_e32 v183, s47, v174
	ds_read_b128 v[0:3], v182
	ds_read_b128 v[4:7], v182 offset:1024
	ds_read_b128 v[8:11], v182 offset:2048
	ds_read_b128 v[12:15], v182 offset:3072
	s_waitcnt vmcnt(0)
	ds_read_b128 v[16:19], v183
	ds_read_b128 v[20:23], v183 offset:1024
	ds_read_b128 v[24:27], v183 offset:2048
	ds_read_b128 v[28:31], v183 offset:3072
	v_mov_b64_e32 v[184:185], 0x100
	s_add_u32 s6, s4, 0x10080
	s_addc_u32 s7, s5, 0
	s_add_i32 s74, s62, 0xc000
	s_mov_b32 m0, s74
	ds_read_b128 v[32:35], v175
	ds_read_b128 v[36:39], v175 offset:1024
	ds_read_b128 v[40:43], v175 offset:2048
	ds_read_b128 v[44:47], v175 offset:3072
	ds_read_b128 v[48:51], v175 offset:4096
	ds_read_b128 v[52:55], v175 offset:5120
	ds_read_b128 v[56:59], v175 offset:6144
	ds_read_b128 v[60:63], v175 offset:7168
	global_load_lds_dwordx4 v160, s[6:7]
	v_lshl_add_u64 v[64:65], s[6:7], 0, v[158:159]
	s_add_i32 s6, s62, 0xe000
	s_mov_b32 m0, s6
	s_nop 0
	global_load_lds_dwordx4 v[64:65], off
	s_waitcnt vmcnt(8)
	s_waitcnt lgkmcnt(0)
	s_barrier
	s_setprio 1
	s_waitcnt lgkmcnt(0)
	v_mfma_f32_16x16x32_bf16 v[64:67], v[0:3], v[32:35], 0
	v_mfma_f32_16x16x32_bf16 v[68:71], v[8:11], v[32:35], 0
	v_mfma_f32_16x16x32_bf16 v[72:75], v[0:3], v[40:43], 0
	v_mfma_f32_16x16x32_bf16 v[76:79], v[8:11], v[40:43], 0
	v_mfma_f32_16x16x32_bf16 v[80:83], v[0:3], v[48:51], 0
	v_mfma_f32_16x16x32_bf16 v[84:87], v[8:11], v[48:51], 0
	v_mfma_f32_16x16x32_bf16 v[88:91], v[0:3], v[56:59], 0
	v_mfma_f32_16x16x32_bf16 v[92:95], v[8:11], v[56:59], 0
	v_mfma_f32_16x16x32_bf16 v[64:67], v[4:7], v[36:39], v[64:67]
	v_mfma_f32_16x16x32_bf16 v[68:71], v[12:15], v[36:39], v[68:71]
	v_mfma_f32_16x16x32_bf16 v[72:75], v[4:7], v[44:47], v[72:75]
	v_mfma_f32_16x16x32_bf16 v[76:79], v[12:15], v[44:47], v[76:79]
	v_mfma_f32_16x16x32_bf16 v[80:83], v[4:7], v[52:55], v[80:83]
	v_mfma_f32_16x16x32_bf16 v[84:87], v[12:15], v[52:55], v[84:87]
	v_mfma_f32_16x16x32_bf16 v[88:91], v[4:7], v[60:63], v[88:91]
	v_mfma_f32_16x16x32_bf16 v[92:95], v[12:15], v[60:63], v[92:95]
	s_setprio 0
	s_setprio 1
	v_mfma_f32_16x16x32_bf16 v[96:99], v[16:19], v[32:35], 0
	v_mfma_f32_16x16x32_bf16 v[32:35], v[24:27], v[32:35], 0
	v_mfma_f32_16x16x32_bf16 v[96:99], v[20:23], v[36:39], v[96:99]
	v_mfma_f32_16x16x32_bf16 v[32:35], v[28:31], v[36:39], v[32:35]
	v_mfma_f32_16x16x32_bf16 v[36:39], v[16:19], v[40:43], 0
	v_mfma_f32_16x16x32_bf16 v[40:43], v[24:27], v[40:43], 0
	v_mfma_f32_16x16x32_bf16 v[36:39], v[20:23], v[44:47], v[36:39]
	v_mfma_f32_16x16x32_bf16 v[40:43], v[28:31], v[44:47], v[40:43]
	v_mfma_f32_16x16x32_bf16 v[44:47], v[16:19], v[48:51], 0
	v_mfma_f32_16x16x32_bf16 v[48:51], v[24:27], v[48:51], 0
	v_mfma_f32_16x16x32_bf16 v[44:47], v[20:23], v[52:55], v[44:47]
	v_mfma_f32_16x16x32_bf16 v[48:51], v[28:31], v[52:55], v[48:51]
	v_mfma_f32_16x16x32_bf16 v[52:55], v[16:19], v[56:59], 0
	v_mfma_f32_16x16x32_bf16 v[56:59], v[24:27], v[56:59], 0
	v_mfma_f32_16x16x32_bf16 v[52:55], v[20:23], v[60:63], v[52:55]
	v_mfma_f32_16x16x32_bf16 v[56:59], v[28:31], v[60:63], v[56:59]
	s_setprio 0
	s_barrier
	s_add_i32 s72, s72, s61
	v_lshl_add_u64 v[178:179], s[0:1], 0, v[176:177]
	s_add_i32 s7, s72, 0x2000
	v_lshl_add_u64 v[128:129], v[178:179], 0, s[58:59]
	s_mov_b32 m0, s72
	v_lshl_add_u64 v[180:181], s[0:1], 0, v[156:157]
	s_add_u32 s86, s0, 0x10100
	ds_read_b128 v[60:63], v175 offset:16384
	ds_read_b128 v[100:103], v175 offset:17408
	ds_read_b128 v[104:107], v175 offset:18432
	ds_read_b128 v[108:111], v175 offset:19456
	ds_read_b128 v[112:115], v175 offset:20480
	ds_read_b128 v[116:119], v175 offset:21504
	ds_read_b128 v[120:123], v175 offset:22528
	ds_read_b128 v[124:127], v175 offset:23552
	global_load_lds_dwordx4 v[128:129], off
	v_lshl_add_u64 v[128:129], v[180:181], 0, s[58:59]
	s_mov_b32 m0, s7
	s_addc_u32 s87, s1, 0
	s_add_i32 s47, s47, s61
	global_load_lds_dwordx4 v[128:129], off
	s_mov_b32 m0, s47
	s_add_i32 s49, s47, 0x2000
	global_load_lds_dwordx4 v176, s[86:87]
	s_mov_b32 m0, s49
	v_lshl_add_u64 v[186:187], s[4:5], 0, v[160:161]
	global_load_lds_dwordx4 v156, s[86:87]
	v_lshl_add_u64 v[128:129], v[186:187], 0, s[58:59]
	s_mov_b32 m0, s62
	v_lshl_add_u64 v[188:189], s[4:5], 0, v[158:159]
	global_load_lds_dwordx4 v[128:129], off
	v_lshl_add_u64 v[128:129], v[188:189], 0, s[58:59]
	s_mov_b32 m0, s63
	s_nop 0
	global_load_lds_dwordx4 v[128:129], off
	s_waitcnt vmcnt(8)
	s_waitcnt lgkmcnt(0)
	s_barrier
	s_setprio 1
	s_waitcnt lgkmcnt(0)
	v_mfma_f32_16x16x32_bf16 v[128:131], v[0:3], v[60:63], 0
	v_mfma_f32_16x16x32_bf16 v[136:139], v[0:3], v[104:107], 0
	v_mfma_f32_16x16x32_bf16 v[144:147], v[0:3], v[112:115], 0
	v_mfma_f32_16x16x32_bf16 v[0:3], v[0:3], v[120:123], 0
	v_mfma_f32_16x16x32_bf16 v[128:131], v[4:7], v[100:103], v[128:131]
	v_mfma_f32_16x16x32_bf16 v[136:139], v[4:7], v[108:111], v[136:139]
	v_mfma_f32_16x16x32_bf16 v[144:147], v[4:7], v[116:119], v[144:147]
	v_mfma_f32_16x16x32_bf16 v[148:151], v[8:11], v[112:115], 0
	v_mfma_f32_16x16x32_bf16 v[0:3], v[4:7], v[124:127], v[0:3]
	v_mfma_f32_16x16x32_bf16 v[4:7], v[8:11], v[120:123], 0
	v_mfma_f32_16x16x32_bf16 v[132:135], v[8:11], v[60:63], 0
	v_mfma_f32_16x16x32_bf16 v[140:143], v[8:11], v[104:107], 0
	v_mfma_f32_16x16x32_bf16 v[148:151], v[12:15], v[116:119], v[148:151]
	v_mfma_f32_16x16x32_bf16 v[4:7], v[12:15], v[124:127], v[4:7]
	v_mfma_f32_16x16x32_bf16 v[132:135], v[12:15], v[100:103], v[132:135]
	v_mfma_f32_16x16x32_bf16 v[140:143], v[12:15], v[108:111], v[140:143]
	s_setprio 0
	s_setprio 1
	v_mfma_f32_16x16x32_bf16 v[8:11], v[16:19], v[60:63], 0
	v_mfma_f32_16x16x32_bf16 v[12:15], v[24:27], v[60:63], 0
	v_mfma_f32_16x16x32_bf16 v[8:11], v[20:23], v[100:103], v[8:11]
	v_mfma_f32_16x16x32_bf16 v[12:15], v[28:31], v[100:103], v[12:15]
	v_mfma_f32_16x16x32_bf16 v[60:63], v[16:19], v[104:107], 0
	v_mfma_f32_16x16x32_bf16 v[100:103], v[24:27], v[104:107], 0
	v_mfma_f32_16x16x32_bf16 v[104:107], v[16:19], v[112:115], 0
	v_mfma_f32_16x16x32_bf16 v[16:19], v[16:19], v[120:123], 0
	v_mfma_f32_16x16x32_bf16 v[60:63], v[20:23], v[108:111], v[60:63]
	v_mfma_f32_16x16x32_bf16 v[100:103], v[28:31], v[108:111], v[100:103]
	v_mfma_f32_16x16x32_bf16 v[104:107], v[20:23], v[116:119], v[104:107]
	v_mfma_f32_16x16x32_bf16 v[108:111], v[24:27], v[112:115], 0
	v_mfma_f32_16x16x32_bf16 v[16:19], v[20:23], v[124:127], v[16:19]
	v_mfma_f32_16x16x32_bf16 v[20:23], v[24:27], v[120:123], 0
	v_mfma_f32_16x16x32_bf16 v[108:111], v[28:31], v[116:119], v[108:111]
	v_mfma_f32_16x16x32_bf16 v[20:23], v[28:31], v[124:127], v[20:23]
	s_setprio 0
	s_barrier
	s_add_i32 s75, 0, 0x18000
	s_add_i32 s88, 0, 0x1c000
	v_add_u32_e32 v226, s75, v174
	v_add_u32_e32 v227, s88, v174
	ds_read_b128 v[24:27], v226
	ds_read_b128 v[28:31], v226 offset:1024
	ds_read_b128 v[112:115], v226 offset:2048
	ds_read_b128 v[116:119], v226 offset:3072
	ds_read_b128 v[120:123], v227
	ds_read_b128 v[124:127], v227 offset:1024
	ds_read_b128 v[152:155], v227 offset:2048
	ds_read_b128 v[162:165], v227 offset:3072
	s_add_u32 s86, s4, 0x10100
	s_addc_u32 s87, s5, 0
	s_mov_b32 m0, s64
	ds_read_b128 v[166:169], v175 offset:32768
	ds_read_b128 v[170:173], v175 offset:33792
	ds_read_b128 v[190:193], v175 offset:34816
	ds_read_b128 v[194:197], v175 offset:35840
	ds_read_b128 v[198:201], v175 offset:36864
	ds_read_b128 v[202:205], v175 offset:37888
	ds_read_b128 v[206:209], v175 offset:38912
	ds_read_b128 v[210:213], v175 offset:39936
	global_load_lds_dwordx4 v160, s[86:87]
	v_lshl_add_u64 v[214:215], s[86:87], 0, v[158:159]
	s_mov_b32 m0, s65
	s_nop 0
	global_load_lds_dwordx4 v158, s[86:87]
	s_waitcnt vmcnt(8)
	s_waitcnt lgkmcnt(0)
	s_barrier
	s_setprio 1
	s_waitcnt lgkmcnt(0)
	v_mfma_f32_16x16x32_bf16 v[64:67], v[24:27], v[166:169], v[64:67]
	v_mfma_f32_16x16x32_bf16 v[68:71], v[112:115], v[166:169], v[68:71]
	v_mfma_f32_16x16x32_bf16 v[72:75], v[24:27], v[190:193], v[72:75]
	v_mfma_f32_16x16x32_bf16 v[76:79], v[112:115], v[190:193], v[76:79]
	v_mfma_f32_16x16x32_bf16 v[80:83], v[24:27], v[198:201], v[80:83]
	v_mfma_f32_16x16x32_bf16 v[84:87], v[112:115], v[198:201], v[84:87]
	v_mfma_f32_16x16x32_bf16 v[88:91], v[24:27], v[206:209], v[88:91]
	v_mfma_f32_16x16x32_bf16 v[92:95], v[112:115], v[206:209], v[92:95]
	v_mfma_f32_16x16x32_bf16 v[64:67], v[28:31], v[170:173], v[64:67]
	v_mfma_f32_16x16x32_bf16 v[68:71], v[116:119], v[170:173], v[68:71]
	v_mfma_f32_16x16x32_bf16 v[72:75], v[28:31], v[194:197], v[72:75]
	v_mfma_f32_16x16x32_bf16 v[76:79], v[116:119], v[194:197], v[76:79]
	v_mfma_f32_16x16x32_bf16 v[80:83], v[28:31], v[202:205], v[80:83]
	v_mfma_f32_16x16x32_bf16 v[84:87], v[116:119], v[202:205], v[84:87]
	v_mfma_f32_16x16x32_bf16 v[88:91], v[28:31], v[210:213], v[88:91]
	v_mfma_f32_16x16x32_bf16 v[92:95], v[116:119], v[210:213], v[92:95]
	s_setprio 0
	s_setprio 1
	v_mfma_f32_16x16x32_bf16 v[96:99], v[120:123], v[166:169], v[96:99]
	v_mfma_f32_16x16x32_bf16 v[32:35], v[152:155], v[166:169], v[32:35]
	v_mfma_f32_16x16x32_bf16 v[36:39], v[120:123], v[190:193], v[36:39]
	v_mfma_f32_16x16x32_bf16 v[40:43], v[152:155], v[190:193], v[40:43]
	v_mfma_f32_16x16x32_bf16 v[44:47], v[120:123], v[198:201], v[44:47]
	v_mfma_f32_16x16x32_bf16 v[48:51], v[152:155], v[198:201], v[48:51]
	v_mfma_f32_16x16x32_bf16 v[52:55], v[120:123], v[206:209], v[52:55]
	v_mfma_f32_16x16x32_bf16 v[56:59], v[152:155], v[206:209], v[56:59]
	v_mfma_f32_16x16x32_bf16 v[96:99], v[124:127], v[170:173], v[96:99]
	v_mfma_f32_16x16x32_bf16 v[32:35], v[162:165], v[170:173], v[32:35]
	v_mfma_f32_16x16x32_bf16 v[36:39], v[124:127], v[194:197], v[36:39]
	v_mfma_f32_16x16x32_bf16 v[40:43], v[162:165], v[194:197], v[40:43]
	v_mfma_f32_16x16x32_bf16 v[44:47], v[124:127], v[202:205], v[44:47]
	v_mfma_f32_16x16x32_bf16 v[48:51], v[162:165], v[202:205], v[48:51]
	v_mfma_f32_16x16x32_bf16 v[52:55], v[124:127], v[210:213], v[52:55]
	v_mfma_f32_16x16x32_bf16 v[56:59], v[162:165], v[210:213], v[56:59]
	s_setprio 0
	s_barrier
	s_add_i32 s75, s75, s61
	s_add_i32 s73, s75, 0x2000
	v_lshl_add_u64 v[178:179], v[178:179], 0, s[44:45]
	s_mov_b32 m0, s75
	s_add_u32 s86, s0, 0x10180
	ds_read_b128 v[166:169], v175 offset:49152
	ds_read_b128 v[170:173], v175 offset:50176
	ds_read_b128 v[190:193], v175 offset:51200
	ds_read_b128 v[194:197], v175 offset:52224
	ds_read_b128 v[198:201], v175 offset:53248
	ds_read_b128 v[202:205], v175 offset:54272
	ds_read_b128 v[206:209], v175 offset:55296
	ds_read_b128 v[210:213], v175 offset:56320
	global_load_lds_dwordx4 v[178:179], off
	v_lshl_add_u64 v[178:179], v[180:181], 0, s[44:45]
	s_mov_b32 m0, s73
	s_addc_u32 s87, s1, 0
	s_add_i32 s0, s88, s61
	global_load_lds_dwordx4 v[178:179], off
	s_mov_b32 m0, s0
	s_add_i32 s1, s0, 0x2000
	global_load_lds_dwordx4 v176, s[86:87]
	s_mov_b32 m0, s1
	s_nop 0
	global_load_lds_dwordx4 v156, s[86:87]
	v_lshl_add_u64 v[178:179], v[186:187], 0, s[44:45]
	s_mov_b32 m0, s68
	s_nop 0
	global_load_lds_dwordx4 v[178:179], off
	v_lshl_add_u64 v[178:179], v[188:189], 0, s[44:45]
	s_mov_b32 m0, s69
	s_nop 0
	global_load_lds_dwordx4 v[178:179], off
	s_waitcnt vmcnt(8)
	s_waitcnt lgkmcnt(0)
	s_barrier
	s_setprio 1
	s_waitcnt lgkmcnt(0)
	v_mfma_f32_16x16x32_bf16 v[148:151], v[112:115], v[198:201], v[148:151]
	v_mfma_f32_16x16x32_bf16 v[0:3], v[24:27], v[206:209], v[0:3]
	v_mfma_f32_16x16x32_bf16 v[4:7], v[112:115], v[206:209], v[4:7]
	v_mfma_f32_16x16x32_bf16 v[128:131], v[24:27], v[166:169], v[128:131]
	v_mfma_f32_16x16x32_bf16 v[132:135], v[112:115], v[166:169], v[132:135]
	v_mfma_f32_16x16x32_bf16 v[136:139], v[24:27], v[190:193], v[136:139]
	v_mfma_f32_16x16x32_bf16 v[140:143], v[112:115], v[190:193], v[140:143]
	v_mfma_f32_16x16x32_bf16 v[144:147], v[24:27], v[198:201], v[144:147]
	v_mfma_f32_16x16x32_bf16 v[148:151], v[116:119], v[202:205], v[148:151]
	v_mfma_f32_16x16x32_bf16 v[0:3], v[28:31], v[210:213], v[0:3]
	v_mfma_f32_16x16x32_bf16 v[4:7], v[116:119], v[210:213], v[4:7]
	v_mfma_f32_16x16x32_bf16 v[128:131], v[28:31], v[170:173], v[128:131]
	v_mfma_f32_16x16x32_bf16 v[132:135], v[116:119], v[170:173], v[132:135]
	v_mfma_f32_16x16x32_bf16 v[136:139], v[28:31], v[194:197], v[136:139]
	v_mfma_f32_16x16x32_bf16 v[140:143], v[116:119], v[194:197], v[140:143]
	v_mfma_f32_16x16x32_bf16 v[144:147], v[28:31], v[202:205], v[144:147]
	s_setprio 0
	s_setprio 1
	v_mfma_f32_16x16x32_bf16 v[8:11], v[120:123], v[166:169], v[8:11]
	v_mfma_f32_16x16x32_bf16 v[12:15], v[152:155], v[166:169], v[12:15]
	v_mfma_f32_16x16x32_bf16 v[24:27], v[120:123], v[190:193], v[60:63]
	v_mfma_f32_16x16x32_bf16 v[28:31], v[152:155], v[190:193], v[100:103]
	v_mfma_f32_16x16x32_bf16 v[60:63], v[120:123], v[198:201], v[104:107]
	v_mfma_f32_16x16x32_bf16 v[100:103], v[152:155], v[198:201], v[108:111]
	v_mfma_f32_16x16x32_bf16 v[16:19], v[120:123], v[206:209], v[16:19]
	v_mfma_f32_16x16x32_bf16 v[20:23], v[152:155], v[206:209], v[20:23]
	v_mfma_f32_16x16x32_bf16 v[8:11], v[124:127], v[170:173], v[8:11]
	v_mfma_f32_16x16x32_bf16 v[12:15], v[162:165], v[170:173], v[12:15]
	v_mfma_f32_16x16x32_bf16 v[24:27], v[124:127], v[194:197], v[24:27]
	v_mfma_f32_16x16x32_bf16 v[28:31], v[162:165], v[194:197], v[28:31]
	v_mfma_f32_16x16x32_bf16 v[60:63], v[124:127], v[202:205], v[60:63]
	v_mfma_f32_16x16x32_bf16 v[100:103], v[162:165], v[202:205], v[100:103]
	v_mfma_f32_16x16x32_bf16 v[16:19], v[124:127], v[210:213], v[16:19]
	v_mfma_f32_16x16x32_bf16 v[20:23], v[162:165], v[210:213], v[20:23]
	s_setprio 0
	s_barrier
	ds_read_b128 v[104:107], v182
	ds_read_b128 v[108:111], v182 offset:1024
	ds_read_b128 v[112:115], v182 offset:2048
	ds_read_b128 v[116:119], v182 offset:3072
	ds_read_b128 v[120:123], v183
	ds_read_b128 v[124:127], v183 offset:1024
	ds_read_b128 v[152:155], v183 offset:2048
	ds_read_b128 v[162:165], v183 offset:3072
	s_add_u32 s4, s4, 0x10180
	s_addc_u32 s5, s5, 0
	s_mov_b32 m0, s74
	ds_read_b128 v[166:169], v175
	ds_read_b128 v[170:173], v175 offset:1024
	ds_read_b128 v[190:193], v175 offset:2048
	ds_read_b128 v[194:197], v175 offset:3072
	ds_read_b128 v[198:201], v175 offset:4096
	ds_read_b128 v[202:205], v175 offset:5120
	ds_read_b128 v[206:209], v175 offset:6144
	ds_read_b128 v[210:213], v175 offset:7168
	global_load_lds_dwordx4 v160, s[4:5]
	s_mov_b32 m0, s6
	s_nop 0
	global_load_lds_dwordx4 v158, s[4:5]
	s_waitcnt vmcnt(8)
	s_waitcnt lgkmcnt(0)
	s_barrier
	s_setprio 1
	s_waitcnt lgkmcnt(0)
	v_mfma_f32_16x16x32_bf16 v[64:67], v[104:107], v[166:169], v[64:67]
	v_mfma_f32_16x16x32_bf16 v[68:71], v[112:115], v[166:169], v[68:71]
	v_mfma_f32_16x16x32_bf16 v[72:75], v[104:107], v[190:193], v[72:75]
	v_mfma_f32_16x16x32_bf16 v[76:79], v[112:115], v[190:193], v[76:79]
	v_mfma_f32_16x16x32_bf16 v[80:83], v[104:107], v[198:201], v[80:83]
	v_mfma_f32_16x16x32_bf16 v[84:87], v[112:115], v[198:201], v[84:87]
	v_mfma_f32_16x16x32_bf16 v[88:91], v[104:107], v[206:209], v[88:91]
	v_mfma_f32_16x16x32_bf16 v[64:67], v[108:111], v[170:173], v[64:67]
	v_mfma_f32_16x16x32_bf16 v[68:71], v[116:119], v[170:173], v[68:71]
	v_mfma_f32_16x16x32_bf16 v[72:75], v[108:111], v[194:197], v[72:75]
	v_mfma_f32_16x16x32_bf16 v[76:79], v[116:119], v[194:197], v[76:79]
	v_mfma_f32_16x16x32_bf16 v[80:83], v[108:111], v[202:205], v[80:83]
	v_mfma_f32_16x16x32_bf16 v[84:87], v[116:119], v[202:205], v[84:87]
	v_mfma_f32_16x16x32_bf16 v[214:217], v[108:111], v[210:213], v[88:91]
	v_mfma_f32_16x16x32_bf16 v[88:91], v[112:115], v[206:209], v[92:95]
	v_mfma_f32_16x16x32_bf16 v[218:221], v[116:119], v[210:213], v[88:91]
	s_setprio 0
	s_setprio 1
	v_mfma_f32_16x16x32_bf16 v[88:91], v[120:123], v[166:169], v[96:99]
	v_mfma_f32_16x16x32_bf16 v[32:35], v[152:155], v[166:169], v[32:35]
	v_mfma_f32_16x16x32_bf16 v[36:39], v[120:123], v[190:193], v[36:39]
	v_mfma_f32_16x16x32_bf16 v[40:43], v[152:155], v[190:193], v[40:43]
	v_mfma_f32_16x16x32_bf16 v[44:47], v[120:123], v[198:201], v[44:47]
	v_mfma_f32_16x16x32_bf16 v[48:51], v[152:155], v[198:201], v[48:51]
	v_mfma_f32_16x16x32_bf16 v[52:55], v[120:123], v[206:209], v[52:55]
	v_mfma_f32_16x16x32_bf16 v[56:59], v[152:155], v[206:209], v[56:59]
	v_mfma_f32_16x16x32_bf16 v[96:99], v[124:127], v[170:173], v[88:91]
	v_mfma_f32_16x16x32_bf16 v[32:35], v[162:165], v[170:173], v[32:35]
	v_mfma_f32_16x16x32_bf16 v[36:39], v[124:127], v[194:197], v[36:39]
	v_mfma_f32_16x16x32_bf16 v[40:43], v[162:165], v[194:197], v[40:43]
	v_mfma_f32_16x16x32_bf16 v[44:47], v[124:127], v[202:205], v[44:47]
	v_mfma_f32_16x16x32_bf16 v[48:51], v[162:165], v[202:205], v[48:51]
	v_mfma_f32_16x16x32_bf16 v[52:55], v[124:127], v[210:213], v[52:55]
	v_mfma_f32_16x16x32_bf16 v[56:59], v[162:165], v[210:213], v[56:59]
	s_setprio 0
	s_barrier
	s_mov_b32 m0, s72
	v_lshl_add_u64 v[248:249], s[54:55], 0, v[176:177]
	s_add_u32 s4, s54, 0x10000
	ds_read_b128 v[88:91], v175 offset:16384
	ds_read_b128 v[92:95], v175 offset:17408
	ds_read_b128 v[166:169], v175 offset:18432
	ds_read_b128 v[170:173], v175 offset:19456
	ds_read_b128 v[190:193], v175 offset:20480
	ds_read_b128 v[194:197], v175 offset:21504
	ds_read_b128 v[198:201], v175 offset:22528
	ds_read_b128 v[202:205], v175 offset:23552
	global_load_lds_dwordx4 v176, s[54:55]
	v_lshl_add_u64 v[250:251], s[54:55], 0, v[156:157]
	s_mov_b32 m0, s7
	s_addc_u32 s5, s55, 0
	global_load_lds_dwordx4 v156, s[54:55]
	s_mov_b32 m0, s47
	v_lshl_add_u64 v[242:243], s[56:57], 0, v[160:161]
	global_load_lds_dwordx4 v176, s[4:5]
	s_mov_b32 m0, s49
	v_lshl_add_u64 v[182:183], s[56:57], 0, v[158:159]
	global_load_lds_dwordx4 v156, s[4:5]
	s_mov_b32 m0, s62
	s_nop 0
	global_load_lds_dwordx4 v160, s[56:57]
	s_mov_b32 m0, s63
	s_nop 0
	global_load_lds_dwordx4 v158, s[56:57]
	s_waitcnt vmcnt(8)
	s_waitcnt lgkmcnt(0)
	s_barrier
	s_setprio 1
	s_waitcnt lgkmcnt(0)
	v_mfma_f32_16x16x32_bf16 v[0:3], v[104:107], v[198:201], v[0:3]
	v_mfma_f32_16x16x32_bf16 v[4:7], v[112:115], v[198:201], v[4:7]
	v_mfma_f32_16x16x32_bf16 v[128:131], v[104:107], v[88:91], v[128:131]
	v_mfma_f32_16x16x32_bf16 v[132:135], v[112:115], v[88:91], v[132:135]
	v_mfma_f32_16x16x32_bf16 v[136:139], v[104:107], v[166:169], v[136:139]
	v_mfma_f32_16x16x32_bf16 v[140:143], v[112:115], v[166:169], v[140:143]
	v_mfma_f32_16x16x32_bf16 v[144:147], v[104:107], v[190:193], v[144:147]
	v_mfma_f32_16x16x32_bf16 v[148:151], v[112:115], v[190:193], v[148:151]
	v_mfma_f32_16x16x32_bf16 v[0:3], v[108:111], v[202:205], v[0:3]
	v_mfma_f32_16x16x32_bf16 v[4:7], v[116:119], v[202:205], v[4:7]
	v_mfma_f32_16x16x32_bf16 v[128:131], v[108:111], v[92:95], v[128:131]
	v_mfma_f32_16x16x32_bf16 v[132:135], v[116:119], v[92:95], v[132:135]
	v_mfma_f32_16x16x32_bf16 v[136:139], v[108:111], v[170:173], v[136:139]
	v_mfma_f32_16x16x32_bf16 v[140:143], v[116:119], v[170:173], v[140:143]
	v_mfma_f32_16x16x32_bf16 v[144:147], v[108:111], v[194:197], v[144:147]
	v_mfma_f32_16x16x32_bf16 v[206:209], v[116:119], v[194:197], v[148:151]
	s_setprio 0
	s_setprio 1
	v_mfma_f32_16x16x32_bf16 v[8:11], v[120:123], v[88:91], v[8:11]
	v_mfma_f32_16x16x32_bf16 v[116:119], v[124:127], v[92:95], v[8:11]
	v_mfma_f32_16x16x32_bf16 v[8:11], v[152:155], v[88:91], v[12:15]
	v_mfma_f32_16x16x32_bf16 v[210:213], v[162:165], v[92:95], v[8:11]
	v_mfma_f32_16x16x32_bf16 v[8:11], v[120:123], v[166:169], v[24:27]
	v_mfma_f32_16x16x32_bf16 v[222:225], v[124:127], v[170:173], v[8:11]
	v_mfma_f32_16x16x32_bf16 v[8:11], v[152:155], v[166:169], v[28:31]
	v_mfma_f32_16x16x32_bf16 v[166:169], v[162:165], v[170:173], v[8:11]
	v_mfma_f32_16x16x32_bf16 v[8:11], v[120:123], v[190:193], v[60:63]
	v_mfma_f32_16x16x32_bf16 v[170:173], v[124:127], v[194:197], v[8:11]
	v_mfma_f32_16x16x32_bf16 v[8:11], v[152:155], v[190:193], v[100:103]
	v_mfma_f32_16x16x32_bf16 v[190:193], v[162:165], v[194:197], v[8:11]
	v_mfma_f32_16x16x32_bf16 v[8:11], v[120:123], v[198:201], v[16:19]
	v_mfma_f32_16x16x32_bf16 v[120:123], v[124:127], v[202:205], v[8:11]
	v_mfma_f32_16x16x32_bf16 v[8:11], v[152:155], v[198:201], v[20:23]
	v_mfma_f32_16x16x32_bf16 v[162:165], v[162:165], v[202:205], v[8:11]
	s_setprio 0
	s_barrier
	s_nop 4
	ds_read_b128 v[8:11], v226
	ds_read_b128 v[12:15], v226 offset:1024
	ds_read_b128 v[16:19], v226 offset:2048
	ds_read_b128 v[20:23], v226 offset:3072
	ds_read_b128 v[194:197], v227
	ds_read_b128 v[198:201], v227 offset:1024
	ds_read_b128 v[202:205], v227 offset:2048
	ds_read_b128 v[226:229], v227 offset:3072
	s_add_u32 s4, s56, 0x10000
	s_addc_u32 s5, s57, 0
	s_mov_b32 m0, s64
	ds_read_b128 v[24:27], v175 offset:32768
	ds_read_b128 v[28:31], v175 offset:33792
	ds_read_b128 v[60:63], v175 offset:34816
	ds_read_b128 v[230:233], v175 offset:35840
	ds_read_b128 v[234:237], v175 offset:36864
	ds_read_b128 v[238:241], v175 offset:37888
	ds_read_b128 v[178:181], v175 offset:38912
	ds_read_b128 v[186:189], v175 offset:39936
	global_load_lds_dwordx4 v160, s[4:5]
	v_lshl_add_u64 v[88:89], s[4:5], 0, v[158:159]
	s_mov_b32 m0, s65
	s_nop 0
	global_load_lds_dwordx4 v158, s[4:5]
	s_waitcnt vmcnt(8)
	s_waitcnt lgkmcnt(0)
	s_barrier
	s_setprio 1
	s_waitcnt lgkmcnt(0)
	v_mfma_f32_16x16x32_bf16 v[64:67], v[8:11], v[24:27], v[64:67]
	v_mfma_f32_16x16x32_bf16 v[152:155], v[12:15], v[28:31], v[64:67]
	v_mfma_f32_16x16x32_bf16 v[64:67], v[16:19], v[24:27], v[68:71]
	v_mfma_f32_16x16x32_bf16 v[148:151], v[20:23], v[28:31], v[64:67]
	v_mfma_f32_16x16x32_bf16 v[64:67], v[8:11], v[60:63], v[72:75]
	v_mfma_f32_16x16x32_bf16 v[108:111], v[12:15], v[230:233], v[64:67]
	v_mfma_f32_16x16x32_bf16 v[64:67], v[16:19], v[60:63], v[76:79]
	v_mfma_f32_16x16x32_bf16 v[104:107], v[20:23], v[230:233], v[64:67]
	v_mfma_f32_16x16x32_bf16 v[64:67], v[8:11], v[234:237], v[80:83]
	v_mfma_f32_16x16x32_bf16 v[92:95], v[12:15], v[238:241], v[64:67]
	v_mfma_f32_16x16x32_bf16 v[64:67], v[16:19], v[234:237], v[84:87]
	v_mfma_f32_16x16x32_bf16 v[88:91], v[20:23], v[238:241], v[64:67]
	v_mfma_f32_16x16x32_bf16 v[64:67], v[8:11], v[178:181], v[214:217]
	v_mfma_f32_16x16x32_bf16 v[76:79], v[12:15], v[186:189], v[64:67]
	v_mfma_f32_16x16x32_bf16 v[64:67], v[16:19], v[178:181], v[218:221]
	v_mfma_f32_16x16x32_bf16 v[72:75], v[20:23], v[186:189], v[64:67]
	s_setprio 0
	s_setprio 1
	v_mfma_f32_16x16x32_bf16 v[64:67], v[194:197], v[24:27], v[96:99]
	v_mfma_f32_16x16x32_bf16 v[24:27], v[202:205], v[24:27], v[32:35]
	v_mfma_f32_16x16x32_bf16 v[112:115], v[226:229], v[28:31], v[24:27]
	v_mfma_f32_16x16x32_bf16 v[24:27], v[194:197], v[60:63], v[36:39]
	v_mfma_f32_16x16x32_bf16 v[100:103], v[198:201], v[230:233], v[24:27]
	v_mfma_f32_16x16x32_bf16 v[24:27], v[202:205], v[60:63], v[40:43]
	v_mfma_f32_16x16x32_bf16 v[96:99], v[226:229], v[230:233], v[24:27]
	v_mfma_f32_16x16x32_bf16 v[24:27], v[194:197], v[234:237], v[44:47]
	v_mfma_f32_16x16x32_bf16 v[84:87], v[198:201], v[238:241], v[24:27]
	v_mfma_f32_16x16x32_bf16 v[24:27], v[202:205], v[234:237], v[48:51]
	v_mfma_f32_16x16x32_bf16 v[80:83], v[226:229], v[238:241], v[24:27]
	v_mfma_f32_16x16x32_bf16 v[24:27], v[194:197], v[178:181], v[52:55]
	v_mfma_f32_16x16x32_bf16 v[68:71], v[198:201], v[186:189], v[24:27]
	v_mfma_f32_16x16x32_bf16 v[24:27], v[202:205], v[178:181], v[56:59]
	v_mfma_f32_16x16x32_bf16 v[124:127], v[198:201], v[28:31], v[64:67]
	v_mfma_f32_16x16x32_bf16 v[64:67], v[226:229], v[186:189], v[24:27]
	s_setprio 0
	s_barrier
	s_mov_b32 m0, s75
	s_nop 2
	v_lshl_add_u64 v[24:25], v[248:249], 0, s[82:83]
	s_add_u32 s4, s54, 0x10080
	ds_read_b128 v[32:35], v175 offset:49152
	ds_read_b128 v[36:39], v175 offset:50176
	ds_read_b128 v[178:181], v175 offset:51200
	ds_read_b128 v[186:189], v175 offset:52224
	ds_read_b128 v[214:217], v175 offset:53248
	ds_read_b128 v[218:221], v175 offset:54272
	ds_read_b128 v[230:233], v175 offset:55296
	ds_read_b128 v[234:237], v175 offset:56320
	global_load_lds_dwordx4 v[24:25], off
	v_lshl_add_u64 v[24:25], v[250:251], 0, s[82:83]
	s_mov_b32 m0, s73
	s_addc_u32 s5, s55, 0
	global_load_lds_dwordx4 v[24:25], off
	s_mov_b32 m0, s0
	s_nop 0
	global_load_lds_dwordx4 v176, s[4:5]
	s_mov_b32 m0, s1
	s_nop 0
	global_load_lds_dwordx4 v156, s[4:5]
	v_lshl_add_u64 v[24:25], v[242:243], 0, s[82:83]
	s_mov_b32 m0, s68
	s_nop 0
	global_load_lds_dwordx4 v[24:25], off
	v_lshl_add_u64 v[24:25], v[182:183], 0, s[82:83]
	s_mov_b32 m0, s69
	s_nop 0
	global_load_lds_dwordx4 v[24:25], off
	s_waitcnt vmcnt(8)
	s_waitcnt lgkmcnt(0)
	s_barrier
	s_setprio 1
	s_waitcnt lgkmcnt(0)
	v_mfma_f32_16x16x32_bf16 v[24:27], v[8:11], v[32:35], v[128:131]
	v_mfma_f32_16x16x32_bf16 v[60:63], v[12:15], v[36:39], v[24:27]
	v_mfma_f32_16x16x32_bf16 v[24:27], v[16:19], v[32:35], v[132:135]
	v_mfma_f32_16x16x32_bf16 v[56:59], v[20:23], v[36:39], v[24:27]
	v_mfma_f32_16x16x32_bf16 v[24:27], v[8:11], v[178:181], v[136:139]
	v_mfma_f32_16x16x32_bf16 v[44:47], v[12:15], v[186:189], v[24:27]
	v_mfma_f32_16x16x32_bf16 v[24:27], v[16:19], v[178:181], v[140:143]
	v_mfma_f32_16x16x32_bf16 v[40:43], v[20:23], v[186:189], v[24:27]
	v_mfma_f32_16x16x32_bf16 v[24:27], v[8:11], v[214:217], v[144:147]
	v_mfma_f32_16x16x32_bf16 v[0:3], v[8:11], v[230:233], v[0:3]
	v_mfma_f32_16x16x32_bf16 v[28:31], v[12:15], v[218:221], v[24:27]
	v_mfma_f32_16x16x32_bf16 v[24:27], v[16:19], v[214:217], v[206:209]
	v_mfma_f32_16x16x32_bf16 v[12:15], v[12:15], v[234:237], v[0:3]
	v_mfma_f32_16x16x32_bf16 v[0:3], v[16:19], v[230:233], v[4:7]
	v_mfma_f32_16x16x32_bf16 v[24:27], v[20:23], v[218:221], v[24:27]
	v_mfma_f32_16x16x32_bf16 v[8:11], v[20:23], v[234:237], v[0:3]
	s_setprio 0
	s_setprio 1
	v_mfma_f32_16x16x32_bf16 v[0:3], v[194:197], v[32:35], v[116:119]
	v_mfma_f32_16x16x32_bf16 v[52:55], v[198:201], v[36:39], v[0:3]
	v_mfma_f32_16x16x32_bf16 v[0:3], v[202:205], v[32:35], v[210:213]
	v_mfma_f32_16x16x32_bf16 v[48:51], v[226:229], v[36:39], v[0:3]
	v_mfma_f32_16x16x32_bf16 v[0:3], v[194:197], v[178:181], v[222:225]
	v_mfma_f32_16x16x32_bf16 v[36:39], v[198:201], v[186:189], v[0:3]
	v_mfma_f32_16x16x32_bf16 v[0:3], v[202:205], v[178:181], v[166:169]
	v_mfma_f32_16x16x32_bf16 v[32:35], v[226:229], v[186:189], v[0:3]
	v_mfma_f32_16x16x32_bf16 v[0:3], v[194:197], v[214:217], v[170:173]
	v_mfma_f32_16x16x32_bf16 v[20:23], v[198:201], v[218:221], v[0:3]
	v_mfma_f32_16x16x32_bf16 v[0:3], v[202:205], v[214:217], v[190:193]
	v_mfma_f32_16x16x32_bf16 v[16:19], v[226:229], v[218:221], v[0:3]
	v_mfma_f32_16x16x32_bf16 v[0:3], v[194:197], v[230:233], v[120:123]
	v_mfma_f32_16x16x32_bf16 v[4:7], v[198:201], v[234:237], v[0:3]
	v_mfma_f32_16x16x32_bf16 v[0:3], v[202:205], v[230:233], v[162:165]
	v_mfma_f32_16x16x32_bf16 v[0:3], v[226:229], v[234:237], v[0:3]
	s_setprio 0
	s_barrier
	s_andn2_b64 vcc, exec, s[38:39]
	s_cbranch_vccnz .LBB0_573
	s_barrier

.LBB0_589:
	s_ashr_i32 s49, s48, 31
	s_lshl_b64 s[6:7], s[48:49], 17
	s_add_u32 s50, s12, s6
	s_addc_u32 s51, s20, s7
	s_and_b64 s[6:7], s[42:43], exec
	s_cselect_b32 s57, s51, s5
	s_cselect_b32 s56, s50, s4
	s_ashr_i32 s47, s46, 31
	s_lshl_b64 s[6:7], s[46:47], 17
	s_add_u32 s52, s27, s6
	s_addc_u32 s53, s60, s7
	s_and_b64 s[6:7], s[42:43], exec
	s_cselect_b32 s55, s53, s1
	s_cselect_b32 s54, s52, s0
	s_add_i32 s72, 0, 0x10000
	s_add_i32 s47, 0, 0x14000
	v_add_u32_e32 v214, s72, v192
	v_add_u32_e32 v215, s47, v192
	ds_read_b128 v[0:3], v214
	ds_read_b128 v[4:7], v214 offset:1024
	ds_read_b128 v[8:11], v214 offset:2048
	ds_read_b128 v[12:15], v214 offset:3072
	s_waitcnt vmcnt(0)
	ds_read_b128 v[16:19], v215
	ds_read_b128 v[20:23], v215 offset:1024
	ds_read_b128 v[24:27], v215 offset:2048
	ds_read_b128 v[28:31], v215 offset:3072
	v_mov_b64_e32 v[184:185], 0x100
	s_add_u32 s6, s4, 0x10080
	s_addc_u32 s7, s5, 0
	s_add_i32 s74, s62, 0xc000
	s_mov_b32 m0, s74
	ds_read_b128 v[32:35], v193
	ds_read_b128 v[36:39], v193 offset:1024
	ds_read_b128 v[40:43], v193 offset:2048
	ds_read_b128 v[44:47], v193 offset:3072
	ds_read_b128 v[48:51], v193 offset:4096
	ds_read_b128 v[52:55], v193 offset:5120
	ds_read_b128 v[56:59], v193 offset:6144
	ds_read_b128 v[60:63], v193 offset:7168
	global_load_lds_dwordx4 v164, s[6:7]
	v_lshl_add_u64 v[64:65], s[6:7], 0, v[162:163]
	s_add_i32 s6, s62, 0xe000
	s_mov_b32 m0, s6
	s_nop 0
	global_load_lds_dwordx4 v[64:65], off
	s_waitcnt vmcnt(8)
	s_waitcnt lgkmcnt(0)
	s_barrier
	s_setprio 1
	s_waitcnt lgkmcnt(0)
	v_mfma_f32_16x16x32_bf16 v[64:67], v[0:3], v[32:35], 0
	v_mfma_f32_16x16x32_bf16 v[68:71], v[8:11], v[32:35], 0
	v_mfma_f32_16x16x32_bf16 v[72:75], v[0:3], v[40:43], 0
	v_mfma_f32_16x16x32_bf16 v[76:79], v[8:11], v[40:43], 0
	v_mfma_f32_16x16x32_bf16 v[80:83], v[0:3], v[48:51], 0
	v_mfma_f32_16x16x32_bf16 v[84:87], v[8:11], v[48:51], 0
	v_mfma_f32_16x16x32_bf16 v[88:91], v[0:3], v[56:59], 0
	v_mfma_f32_16x16x32_bf16 v[92:95], v[8:11], v[56:59], 0
	v_mfma_f32_16x16x32_bf16 v[64:67], v[4:7], v[36:39], v[64:67]
	v_mfma_f32_16x16x32_bf16 v[68:71], v[12:15], v[36:39], v[68:71]
	v_mfma_f32_16x16x32_bf16 v[72:75], v[4:7], v[44:47], v[72:75]
	v_mfma_f32_16x16x32_bf16 v[76:79], v[12:15], v[44:47], v[76:79]
	v_mfma_f32_16x16x32_bf16 v[80:83], v[4:7], v[52:55], v[80:83]
	v_mfma_f32_16x16x32_bf16 v[84:87], v[12:15], v[52:55], v[84:87]
	v_mfma_f32_16x16x32_bf16 v[88:91], v[4:7], v[60:63], v[88:91]
	v_mfma_f32_16x16x32_bf16 v[92:95], v[12:15], v[60:63], v[92:95]
	s_setprio 0
	s_setprio 1
	v_mfma_f32_16x16x32_bf16 v[96:99], v[16:19], v[32:35], 0
	v_mfma_f32_16x16x32_bf16 v[32:35], v[24:27], v[32:35], 0
	v_mfma_f32_16x16x32_bf16 v[96:99], v[20:23], v[36:39], v[96:99]
	v_mfma_f32_16x16x32_bf16 v[32:35], v[28:31], v[36:39], v[32:35]
	v_mfma_f32_16x16x32_bf16 v[36:39], v[16:19], v[40:43], 0
	v_mfma_f32_16x16x32_bf16 v[40:43], v[24:27], v[40:43], 0
	v_mfma_f32_16x16x32_bf16 v[36:39], v[20:23], v[44:47], v[36:39]
	v_mfma_f32_16x16x32_bf16 v[40:43], v[28:31], v[44:47], v[40:43]
	v_mfma_f32_16x16x32_bf16 v[44:47], v[16:19], v[48:51], 0
	v_mfma_f32_16x16x32_bf16 v[48:51], v[24:27], v[48:51], 0
	v_mfma_f32_16x16x32_bf16 v[44:47], v[20:23], v[52:55], v[44:47]
	v_mfma_f32_16x16x32_bf16 v[48:51], v[28:31], v[52:55], v[48:51]
	v_mfma_f32_16x16x32_bf16 v[52:55], v[16:19], v[56:59], 0
	v_mfma_f32_16x16x32_bf16 v[56:59], v[24:27], v[56:59], 0
	v_mfma_f32_16x16x32_bf16 v[52:55], v[20:23], v[60:63], v[52:55]
	v_mfma_f32_16x16x32_bf16 v[56:59], v[28:31], v[60:63], v[56:59]
	s_setprio 0
	s_barrier
	s_add_i32 s72, s72, s61
	v_lshl_add_u64 v[174:175], s[0:1], 0, v[176:177]
	s_add_i32 s7, s72, 0x2000
	v_lshl_add_u64 v[128:129], v[174:175], 0, s[58:59]
	s_mov_b32 m0, s72
	v_lshl_add_u64 v[182:183], s[0:1], 0, v[160:161]
	s_add_u32 s86, s0, 0x10100
	ds_read_b128 v[60:63], v193 offset:16384
	ds_read_b128 v[100:103], v193 offset:17408
	ds_read_b128 v[104:107], v193 offset:18432
	ds_read_b128 v[108:111], v193 offset:19456
	ds_read_b128 v[112:115], v193 offset:20480
	ds_read_b128 v[116:119], v193 offset:21504
	ds_read_b128 v[120:123], v193 offset:22528
	ds_read_b128 v[124:127], v193 offset:23552
	global_load_lds_dwordx4 v[128:129], off
	v_lshl_add_u64 v[128:129], v[182:183], 0, s[58:59]
	s_mov_b32 m0, s7
	s_addc_u32 s87, s1, 0
	s_add_i32 s47, s47, s61
	global_load_lds_dwordx4 v[128:129], off
	s_mov_b32 m0, s47
	s_add_i32 s49, s47, 0x2000
	global_load_lds_dwordx4 v176, s[86:87]
	s_mov_b32 m0, s49
	v_lshl_add_u64 v[190:191], s[4:5], 0, v[164:165]
	global_load_lds_dwordx4 v160, s[86:87]
	v_lshl_add_u64 v[128:129], v[190:191], 0, s[58:59]
	s_mov_b32 m0, s62
	v_lshl_add_u64 v[210:211], s[4:5], 0, v[162:163]
	global_load_lds_dwordx4 v[128:129], off
	v_lshl_add_u64 v[128:129], v[210:211], 0, s[58:59]
	s_mov_b32 m0, s63
	s_nop 0
	global_load_lds_dwordx4 v[128:129], off
	s_waitcnt vmcnt(8)
	s_waitcnt lgkmcnt(0)
	s_barrier
	s_setprio 1
	s_waitcnt lgkmcnt(0)
	v_mfma_f32_16x16x32_bf16 v[128:131], v[0:3], v[60:63], 0
	v_mfma_f32_16x16x32_bf16 v[136:139], v[0:3], v[104:107], 0
	v_mfma_f32_16x16x32_bf16 v[144:147], v[0:3], v[112:115], 0
	v_mfma_f32_16x16x32_bf16 v[0:3], v[0:3], v[120:123], 0
	v_mfma_f32_16x16x32_bf16 v[128:131], v[4:7], v[100:103], v[128:131]
	v_mfma_f32_16x16x32_bf16 v[132:135], v[8:11], v[60:63], 0
	v_mfma_f32_16x16x32_bf16 v[136:139], v[4:7], v[108:111], v[136:139]
	v_mfma_f32_16x16x32_bf16 v[140:143], v[8:11], v[104:107], 0
	v_mfma_f32_16x16x32_bf16 v[144:147], v[4:7], v[116:119], v[144:147]
	v_mfma_f32_16x16x32_bf16 v[148:151], v[8:11], v[112:115], 0
	v_mfma_f32_16x16x32_bf16 v[0:3], v[4:7], v[124:127], v[0:3]
	v_mfma_f32_16x16x32_bf16 v[4:7], v[8:11], v[120:123], 0
	v_mfma_f32_16x16x32_bf16 v[132:135], v[12:15], v[100:103], v[132:135]
	v_mfma_f32_16x16x32_bf16 v[140:143], v[12:15], v[108:111], v[140:143]
	v_mfma_f32_16x16x32_bf16 v[148:151], v[12:15], v[116:119], v[148:151]
	v_mfma_f32_16x16x32_bf16 v[4:7], v[12:15], v[124:127], v[4:7]
	s_setprio 0
	s_setprio 1
	v_mfma_f32_16x16x32_bf16 v[8:11], v[16:19], v[60:63], 0
	v_mfma_f32_16x16x32_bf16 v[12:15], v[24:27], v[60:63], 0
	v_mfma_f32_16x16x32_bf16 v[8:11], v[20:23], v[100:103], v[8:11]
	v_mfma_f32_16x16x32_bf16 v[12:15], v[28:31], v[100:103], v[12:15]
	v_mfma_f32_16x16x32_bf16 v[60:63], v[16:19], v[104:107], 0
	v_mfma_f32_16x16x32_bf16 v[100:103], v[24:27], v[104:107], 0
	v_mfma_f32_16x16x32_bf16 v[104:107], v[16:19], v[112:115], 0
	v_mfma_f32_16x16x32_bf16 v[16:19], v[16:19], v[120:123], 0
	v_mfma_f32_16x16x32_bf16 v[60:63], v[20:23], v[108:111], v[60:63]
	v_mfma_f32_16x16x32_bf16 v[104:107], v[20:23], v[116:119], v[104:107]
	v_mfma_f32_16x16x32_bf16 v[16:19], v[20:23], v[124:127], v[16:19]
	v_mfma_f32_16x16x32_bf16 v[20:23], v[24:27], v[120:123], 0
	v_mfma_f32_16x16x32_bf16 v[100:103], v[28:31], v[108:111], v[100:103]
	v_mfma_f32_16x16x32_bf16 v[108:111], v[24:27], v[112:115], 0
	v_mfma_f32_16x16x32_bf16 v[20:23], v[28:31], v[124:127], v[20:23]
	v_mfma_f32_16x16x32_bf16 v[108:111], v[28:31], v[116:119], v[108:111]
	s_setprio 0
	s_barrier
	s_add_i32 s75, 0, 0x18000
	s_add_i32 s88, 0, 0x1c000
	v_add_u32_e32 v234, s75, v192
	v_add_u32_e32 v235, s88, v192
	ds_read_b128 v[24:27], v234
	ds_read_b128 v[28:31], v234 offset:1024
	ds_read_b128 v[112:115], v234 offset:2048
	ds_read_b128 v[116:119], v234 offset:3072
	ds_read_b128 v[120:123], v235
	ds_read_b128 v[124:127], v235 offset:1024
	ds_read_b128 v[152:155], v235 offset:2048
	ds_read_b128 v[156:159], v235 offset:3072
	s_add_u32 s86, s4, 0x10100
	s_addc_u32 s87, s5, 0
	s_mov_b32 m0, s64
	ds_read_b128 v[166:169], v193 offset:32768
	ds_read_b128 v[170:173], v193 offset:33792
	ds_read_b128 v[178:181], v193 offset:34816
	ds_read_b128 v[186:189], v193 offset:35840
	ds_read_b128 v[194:197], v193 offset:36864
	ds_read_b128 v[198:201], v193 offset:37888
	ds_read_b128 v[202:205], v193 offset:38912
	ds_read_b128 v[206:209], v193 offset:39936
	global_load_lds_dwordx4 v164, s[86:87]
	v_lshl_add_u64 v[212:213], s[86:87], 0, v[162:163]
	s_mov_b32 m0, s65
	s_nop 0
	global_load_lds_dwordx4 v162, s[86:87]
	s_waitcnt vmcnt(8)
	s_waitcnt lgkmcnt(0)
	s_barrier
	s_setprio 1
	s_waitcnt lgkmcnt(0)
	v_mfma_f32_16x16x32_bf16 v[64:67], v[24:27], v[166:169], v[64:67]
	v_mfma_f32_16x16x32_bf16 v[68:71], v[112:115], v[166:169], v[68:71]
	v_mfma_f32_16x16x32_bf16 v[72:75], v[24:27], v[178:181], v[72:75]
	v_mfma_f32_16x16x32_bf16 v[76:79], v[112:115], v[178:181], v[76:79]
	v_mfma_f32_16x16x32_bf16 v[80:83], v[24:27], v[194:197], v[80:83]
	v_mfma_f32_16x16x32_bf16 v[84:87], v[112:115], v[194:197], v[84:87]
	v_mfma_f32_16x16x32_bf16 v[88:91], v[24:27], v[202:205], v[88:91]
	v_mfma_f32_16x16x32_bf16 v[92:95], v[112:115], v[202:205], v[92:95]
	v_mfma_f32_16x16x32_bf16 v[64:67], v[28:31], v[170:173], v[64:67]
	v_mfma_f32_16x16x32_bf16 v[68:71], v[116:119], v[170:173], v[68:71]
	v_mfma_f32_16x16x32_bf16 v[72:75], v[28:31], v[186:189], v[72:75]
	v_mfma_f32_16x16x32_bf16 v[76:79], v[116:119], v[186:189], v[76:79]
	v_mfma_f32_16x16x32_bf16 v[80:83], v[28:31], v[198:201], v[80:83]
	v_mfma_f32_16x16x32_bf16 v[84:87], v[116:119], v[198:201], v[84:87]
	v_mfma_f32_16x16x32_bf16 v[88:91], v[28:31], v[206:209], v[88:91]
	v_mfma_f32_16x16x32_bf16 v[92:95], v[116:119], v[206:209], v[92:95]
	s_setprio 0
	s_setprio 1
	v_mfma_f32_16x16x32_bf16 v[32:35], v[152:155], v[166:169], v[32:35]
	v_mfma_f32_16x16x32_bf16 v[36:39], v[120:123], v[178:181], v[36:39]
	v_mfma_f32_16x16x32_bf16 v[40:43], v[152:155], v[178:181], v[40:43]
	v_mfma_f32_16x16x32_bf16 v[44:47], v[120:123], v[194:197], v[44:47]
	v_mfma_f32_16x16x32_bf16 v[48:51], v[152:155], v[194:197], v[48:51]
	v_mfma_f32_16x16x32_bf16 v[52:55], v[120:123], v[202:205], v[52:55]
	v_mfma_f32_16x16x32_bf16 v[56:59], v[152:155], v[202:205], v[56:59]
	v_mfma_f32_16x16x32_bf16 v[96:99], v[120:123], v[166:169], v[96:99]
	v_mfma_f32_16x16x32_bf16 v[32:35], v[156:159], v[170:173], v[32:35]
	v_mfma_f32_16x16x32_bf16 v[36:39], v[124:127], v[186:189], v[36:39]
	v_mfma_f32_16x16x32_bf16 v[40:43], v[156:159], v[186:189], v[40:43]
	v_mfma_f32_16x16x32_bf16 v[44:47], v[124:127], v[198:201], v[44:47]
	v_mfma_f32_16x16x32_bf16 v[48:51], v[156:159], v[198:201], v[48:51]
	v_mfma_f32_16x16x32_bf16 v[52:55], v[124:127], v[206:209], v[52:55]
	v_mfma_f32_16x16x32_bf16 v[56:59], v[156:159], v[206:209], v[56:59]
	v_mfma_f32_16x16x32_bf16 v[96:99], v[124:127], v[170:173], v[96:99]
	s_setprio 0
	s_barrier
	s_add_i32 s75, s75, s61
	s_add_i32 s73, s75, 0x2000
	v_lshl_add_u64 v[174:175], v[174:175], 0, s[44:45]
	s_mov_b32 m0, s75
	s_add_u32 s86, s0, 0x10180
	ds_read_b128 v[166:169], v193 offset:49152
	ds_read_b128 v[170:173], v193 offset:50176
	ds_read_b128 v[178:181], v193 offset:51200
	ds_read_b128 v[186:189], v193 offset:52224
	ds_read_b128 v[194:197], v193 offset:53248
	ds_read_b128 v[198:201], v193 offset:54272
	ds_read_b128 v[202:205], v193 offset:55296
	ds_read_b128 v[206:209], v193 offset:56320
	global_load_lds_dwordx4 v[174:175], off
	v_lshl_add_u64 v[174:175], v[182:183], 0, s[44:45]
	s_mov_b32 m0, s73
	s_addc_u32 s87, s1, 0
	s_add_i32 s0, s88, s61
	global_load_lds_dwordx4 v[174:175], off
	s_mov_b32 m0, s0
	s_add_i32 s1, s0, 0x2000
	global_load_lds_dwordx4 v176, s[86:87]
	s_mov_b32 m0, s1
	s_nop 0
	global_load_lds_dwordx4 v160, s[86:87]
	v_lshl_add_u64 v[174:175], v[190:191], 0, s[44:45]
	s_mov_b32 m0, s68
	s_nop 0
	global_load_lds_dwordx4 v[174:175], off
	v_lshl_add_u64 v[174:175], v[210:211], 0, s[44:45]
	s_mov_b32 m0, s69
	s_nop 0
	global_load_lds_dwordx4 v[174:175], off
	s_waitcnt vmcnt(8)
	s_waitcnt lgkmcnt(0)
	s_barrier
	s_setprio 1
	s_waitcnt lgkmcnt(0)
	v_mfma_f32_16x16x32_bf16 v[132:135], v[112:115], v[166:169], v[132:135]
	v_mfma_f32_16x16x32_bf16 v[140:143], v[112:115], v[178:181], v[140:143]
	v_mfma_f32_16x16x32_bf16 v[144:147], v[24:27], v[194:197], v[144:147]
	v_mfma_f32_16x16x32_bf16 v[148:151], v[112:115], v[194:197], v[148:151]
	v_mfma_f32_16x16x32_bf16 v[0:3], v[24:27], v[202:205], v[0:3]
	v_mfma_f32_16x16x32_bf16 v[4:7], v[112:115], v[202:205], v[4:7]
	v_mfma_f32_16x16x32_bf16 v[128:131], v[24:27], v[166:169], v[128:131]
	v_mfma_f32_16x16x32_bf16 v[132:135], v[116:119], v[170:173], v[132:135]
	v_mfma_f32_16x16x32_bf16 v[136:139], v[24:27], v[178:181], v[136:139]
	v_mfma_f32_16x16x32_bf16 v[140:143], v[116:119], v[186:189], v[140:143]
	v_mfma_f32_16x16x32_bf16 v[144:147], v[28:31], v[198:201], v[144:147]
	v_mfma_f32_16x16x32_bf16 v[148:151], v[116:119], v[198:201], v[148:151]
	v_mfma_f32_16x16x32_bf16 v[0:3], v[28:31], v[206:209], v[0:3]
	v_mfma_f32_16x16x32_bf16 v[4:7], v[116:119], v[206:209], v[4:7]
	v_mfma_f32_16x16x32_bf16 v[128:131], v[28:31], v[170:173], v[128:131]
	v_mfma_f32_16x16x32_bf16 v[136:139], v[28:31], v[186:189], v[136:139]
	s_setprio 0
	s_setprio 1
	v_mfma_f32_16x16x32_bf16 v[8:11], v[120:123], v[166:169], v[8:11]
	v_mfma_f32_16x16x32_bf16 v[12:15], v[152:155], v[166:169], v[12:15]
	v_mfma_f32_16x16x32_bf16 v[24:27], v[120:123], v[178:181], v[60:63]
	v_mfma_f32_16x16x32_bf16 v[28:31], v[152:155], v[178:181], v[100:103]
	v_mfma_f32_16x16x32_bf16 v[60:63], v[120:123], v[194:197], v[104:107]
	v_mfma_f32_16x16x32_bf16 v[100:103], v[152:155], v[194:197], v[108:111]
	v_mfma_f32_16x16x32_bf16 v[16:19], v[120:123], v[202:205], v[16:19]
	v_mfma_f32_16x16x32_bf16 v[20:23], v[152:155], v[202:205], v[20:23]
	v_mfma_f32_16x16x32_bf16 v[8:11], v[124:127], v[170:173], v[8:11]
	v_mfma_f32_16x16x32_bf16 v[12:15], v[156:159], v[170:173], v[12:15]
	v_mfma_f32_16x16x32_bf16 v[24:27], v[124:127], v[186:189], v[24:27]
	v_mfma_f32_16x16x32_bf16 v[28:31], v[156:159], v[186:189], v[28:31]
	v_mfma_f32_16x16x32_bf16 v[60:63], v[124:127], v[198:201], v[60:63]
	v_mfma_f32_16x16x32_bf16 v[100:103], v[156:159], v[198:201], v[100:103]
	v_mfma_f32_16x16x32_bf16 v[16:19], v[124:127], v[206:209], v[16:19]
	v_mfma_f32_16x16x32_bf16 v[20:23], v[156:159], v[206:209], v[20:23]
	s_setprio 0
	s_barrier
	ds_read_b128 v[104:107], v214
	ds_read_b128 v[108:111], v214 offset:1024
	ds_read_b128 v[112:115], v214 offset:2048
	ds_read_b128 v[116:119], v214 offset:3072
	ds_read_b128 v[120:123], v215
	ds_read_b128 v[124:127], v215 offset:1024
	ds_read_b128 v[152:155], v215 offset:2048
	ds_read_b128 v[156:159], v215 offset:3072
	s_add_u32 s4, s4, 0x10180
	s_addc_u32 s5, s5, 0
	s_mov_b32 m0, s74
	ds_read_b128 v[166:169], v193
	ds_read_b128 v[170:173], v193 offset:1024
	ds_read_b128 v[178:181], v193 offset:2048
	ds_read_b128 v[186:189], v193 offset:3072
	ds_read_b128 v[194:197], v193 offset:4096
	ds_read_b128 v[198:201], v193 offset:5120
	ds_read_b128 v[202:205], v193 offset:6144
	ds_read_b128 v[206:209], v193 offset:7168
	global_load_lds_dwordx4 v164, s[4:5]
	s_mov_b32 m0, s6
	s_nop 0
	global_load_lds_dwordx4 v162, s[4:5]
	s_waitcnt vmcnt(8)
	s_waitcnt lgkmcnt(0)
	s_barrier
	s_setprio 1
	s_waitcnt lgkmcnt(0)
	v_mfma_f32_16x16x32_bf16 v[64:67], v[104:107], v[166:169], v[64:67]
	v_mfma_f32_16x16x32_bf16 v[68:71], v[112:115], v[166:169], v[68:71]
	v_mfma_f32_16x16x32_bf16 v[72:75], v[104:107], v[178:181], v[72:75]
	v_mfma_f32_16x16x32_bf16 v[76:79], v[112:115], v[178:181], v[76:79]
	v_mfma_f32_16x16x32_bf16 v[80:83], v[104:107], v[194:197], v[80:83]
	v_mfma_f32_16x16x32_bf16 v[84:87], v[112:115], v[194:197], v[84:87]
	v_mfma_f32_16x16x32_bf16 v[88:91], v[104:107], v[202:205], v[88:91]
	v_mfma_f32_16x16x32_bf16 v[64:67], v[108:111], v[170:173], v[64:67]
	v_mfma_f32_16x16x32_bf16 v[68:71], v[116:119], v[170:173], v[68:71]
	v_mfma_f32_16x16x32_bf16 v[72:75], v[108:111], v[186:189], v[72:75]
	v_mfma_f32_16x16x32_bf16 v[76:79], v[116:119], v[186:189], v[76:79]
	v_mfma_f32_16x16x32_bf16 v[80:83], v[108:111], v[198:201], v[80:83]
	v_mfma_f32_16x16x32_bf16 v[84:87], v[116:119], v[198:201], v[84:87]
	v_mfma_f32_16x16x32_bf16 v[210:213], v[108:111], v[206:209], v[88:91]
	v_mfma_f32_16x16x32_bf16 v[88:91], v[112:115], v[202:205], v[92:95]
	v_mfma_f32_16x16x32_bf16 v[214:217], v[116:119], v[206:209], v[88:91]
	s_setprio 0
	s_setprio 1
	v_mfma_f32_16x16x32_bf16 v[32:35], v[152:155], v[166:169], v[32:35]
	v_mfma_f32_16x16x32_bf16 v[36:39], v[120:123], v[178:181], v[36:39]
	v_mfma_f32_16x16x32_bf16 v[40:43], v[152:155], v[178:181], v[40:43]
	v_mfma_f32_16x16x32_bf16 v[44:47], v[120:123], v[194:197], v[44:47]
	v_mfma_f32_16x16x32_bf16 v[48:51], v[152:155], v[194:197], v[48:51]
	v_mfma_f32_16x16x32_bf16 v[52:55], v[120:123], v[202:205], v[52:55]
	v_mfma_f32_16x16x32_bf16 v[56:59], v[152:155], v[202:205], v[56:59]
	v_mfma_f32_16x16x32_bf16 v[88:91], v[120:123], v[166:169], v[96:99]
	v_mfma_f32_16x16x32_bf16 v[32:35], v[156:159], v[170:173], v[32:35]
	v_mfma_f32_16x16x32_bf16 v[36:39], v[124:127], v[186:189], v[36:39]
	v_mfma_f32_16x16x32_bf16 v[40:43], v[156:159], v[186:189], v[40:43]
	v_mfma_f32_16x16x32_bf16 v[44:47], v[124:127], v[198:201], v[44:47]
	v_mfma_f32_16x16x32_bf16 v[48:51], v[156:159], v[198:201], v[48:51]
	v_mfma_f32_16x16x32_bf16 v[52:55], v[124:127], v[206:209], v[52:55]
	v_mfma_f32_16x16x32_bf16 v[56:59], v[156:159], v[206:209], v[56:59]
	v_mfma_f32_16x16x32_bf16 v[96:99], v[124:127], v[170:173], v[88:91]
	s_setprio 0
	s_barrier
	s_mov_b32 m0, s72
	v_lshl_add_u64 v[174:175], s[54:55], 0, v[176:177]
	s_add_u32 s4, s54, 0x10000
	ds_read_b128 v[88:91], v193 offset:16384
	ds_read_b128 v[92:95], v193 offset:17408
	ds_read_b128 v[166:169], v193 offset:18432
	ds_read_b128 v[170:173], v193 offset:19456
	ds_read_b128 v[178:181], v193 offset:20480
	ds_read_b128 v[186:189], v193 offset:21504
	ds_read_b128 v[194:197], v193 offset:22528
	ds_read_b128 v[198:201], v193 offset:23552
	global_load_lds_dwordx4 v176, s[54:55]
	v_lshl_add_u64 v[182:183], s[54:55], 0, v[160:161]
	s_mov_b32 m0, s7
	s_addc_u32 s5, s55, 0
	global_load_lds_dwordx4 v160, s[54:55]
	s_mov_b32 m0, s47
	v_lshl_add_u64 v[242:243], s[56:57], 0, v[162:163]
	global_load_lds_dwordx4 v176, s[4:5]
	s_mov_b32 m0, s49
	s_nop 0
	global_load_lds_dwordx4 v160, s[4:5]
	v_lshl_add_u64 v[190:191], s[56:57], 0, v[164:165]
	s_mov_b32 m0, s62
	s_nop 0
	global_load_lds_dwordx4 v164, s[56:57]
	s_mov_b32 m0, s63
	s_nop 0
	global_load_lds_dwordx4 v162, s[56:57]
	s_waitcnt vmcnt(8)
	s_waitcnt lgkmcnt(0)
	s_barrier
	s_setprio 1
	s_waitcnt lgkmcnt(0)
	v_mfma_f32_16x16x32_bf16 v[132:135], v[112:115], v[88:91], v[132:135]
	v_mfma_f32_16x16x32_bf16 v[202:205], v[116:119], v[92:95], v[132:135]
	v_mfma_f32_16x16x32_bf16 v[132:135], v[104:107], v[166:169], v[136:139]
	v_mfma_f32_16x16x32_bf16 v[136:139], v[108:111], v[170:173], v[132:135]
	v_mfma_f32_16x16x32_bf16 v[132:135], v[112:115], v[166:169], v[140:143]
	v_mfma_f32_16x16x32_bf16 v[206:209], v[116:119], v[170:173], v[132:135]
	v_mfma_f32_16x16x32_bf16 v[132:135], v[104:107], v[178:181], v[144:147]
	v_mfma_f32_16x16x32_bf16 v[0:3], v[104:107], v[194:197], v[0:3]
	v_mfma_f32_16x16x32_bf16 v[4:7], v[112:115], v[194:197], v[4:7]
	v_mfma_f32_16x16x32_bf16 v[128:131], v[104:107], v[88:91], v[128:131]
	v_mfma_f32_16x16x32_bf16 v[218:221], v[108:111], v[186:189], v[132:135]
	v_mfma_f32_16x16x32_bf16 v[132:135], v[112:115], v[178:181], v[148:151]
	v_mfma_f32_16x16x32_bf16 v[0:3], v[108:111], v[198:201], v[0:3]
	v_mfma_f32_16x16x32_bf16 v[4:7], v[116:119], v[198:201], v[4:7]
	v_mfma_f32_16x16x32_bf16 v[128:131], v[108:111], v[92:95], v[128:131]
	v_mfma_f32_16x16x32_bf16 v[222:225], v[116:119], v[186:189], v[132:135]
	s_setprio 0
	s_setprio 1
	v_mfma_f32_16x16x32_bf16 v[8:11], v[120:123], v[88:91], v[8:11]
	v_mfma_f32_16x16x32_bf16 v[108:111], v[124:127], v[92:95], v[8:11]
	v_mfma_f32_16x16x32_bf16 v[8:11], v[152:155], v[88:91], v[12:15]
	v_mfma_f32_16x16x32_bf16 v[226:229], v[156:159], v[92:95], v[8:11]
	v_mfma_f32_16x16x32_bf16 v[8:11], v[120:123], v[166:169], v[24:27]
	v_mfma_f32_16x16x32_bf16 v[230:233], v[124:127], v[170:173], v[8:11]
	v_mfma_f32_16x16x32_bf16 v[8:11], v[152:155], v[166:169], v[28:31]
	v_mfma_f32_16x16x32_bf16 v[166:169], v[156:159], v[170:173], v[8:11]
	v_mfma_f32_16x16x32_bf16 v[8:11], v[120:123], v[178:181], v[60:63]
	v_mfma_f32_16x16x32_bf16 v[170:173], v[124:127], v[186:189], v[8:11]
	v_mfma_f32_16x16x32_bf16 v[8:11], v[152:155], v[178:181], v[100:103]
	v_mfma_f32_16x16x32_bf16 v[178:181], v[156:159], v[186:189], v[8:11]
	v_mfma_f32_16x16x32_bf16 v[8:11], v[120:123], v[194:197], v[16:19]
	v_mfma_f32_16x16x32_bf16 v[120:123], v[124:127], v[198:201], v[8:11]
	v_mfma_f32_16x16x32_bf16 v[8:11], v[152:155], v[194:197], v[20:23]
	v_mfma_f32_16x16x32_bf16 v[124:127], v[156:159], v[198:201], v[8:11]
	s_setprio 0
	s_barrier
	s_nop 4
	ds_read_b128 v[8:11], v234
	ds_read_b128 v[12:15], v234 offset:1024
	ds_read_b128 v[16:19], v234 offset:2048
	ds_read_b128 v[20:23], v234 offset:3072
	ds_read_b128 v[152:155], v235
	ds_read_b128 v[156:159], v235 offset:1024
	ds_read_b128 v[186:189], v235 offset:2048
	ds_read_b128 v[194:197], v235 offset:3072
	s_add_u32 s4, s56, 0x10000
	s_addc_u32 s5, s57, 0
	s_mov_b32 m0, s64
	ds_read_b128 v[24:27], v193 offset:32768
	ds_read_b128 v[28:31], v193 offset:33792
	ds_read_b128 v[60:63], v193 offset:34816
	ds_read_b128 v[100:103], v193 offset:35840
	ds_read_b128 v[198:201], v193 offset:36864
	ds_read_b128 v[234:237], v193 offset:37888
	ds_read_b128 v[238:241], v193 offset:38912
	ds_read_b128 v[248:251], v193 offset:39936
	global_load_lds_dwordx4 v164, s[4:5]
	v_lshl_add_u64 v[88:89], s[4:5], 0, v[162:163]
	s_mov_b32 m0, s65
	s_nop 0
	global_load_lds_dwordx4 v162, s[4:5]
	s_waitcnt vmcnt(8)
	s_waitcnt lgkmcnt(0)
	s_barrier
	s_setprio 1
	s_waitcnt lgkmcnt(0)
	v_mfma_f32_16x16x32_bf16 v[64:67], v[8:11], v[24:27], v[64:67]
	v_mfma_f32_16x16x32_bf16 v[148:151], v[12:15], v[28:31], v[64:67]
	v_mfma_f32_16x16x32_bf16 v[64:67], v[16:19], v[24:27], v[68:71]
	v_mfma_f32_16x16x32_bf16 v[144:147], v[20:23], v[28:31], v[64:67]
	v_mfma_f32_16x16x32_bf16 v[64:67], v[8:11], v[60:63], v[72:75]
	v_mfma_f32_16x16x32_bf16 v[116:119], v[12:15], v[100:103], v[64:67]
	v_mfma_f32_16x16x32_bf16 v[64:67], v[16:19], v[60:63], v[76:79]
	v_mfma_f32_16x16x32_bf16 v[112:115], v[20:23], v[100:103], v[64:67]
	v_mfma_f32_16x16x32_bf16 v[64:67], v[8:11], v[198:201], v[80:83]
	v_mfma_f32_16x16x32_bf16 v[92:95], v[12:15], v[234:237], v[64:67]
	v_mfma_f32_16x16x32_bf16 v[64:67], v[16:19], v[198:201], v[84:87]
	v_mfma_f32_16x16x32_bf16 v[88:91], v[20:23], v[234:237], v[64:67]
	v_mfma_f32_16x16x32_bf16 v[64:67], v[8:11], v[238:241], v[210:213]
	v_mfma_f32_16x16x32_bf16 v[76:79], v[12:15], v[248:251], v[64:67]
	v_mfma_f32_16x16x32_bf16 v[64:67], v[16:19], v[238:241], v[214:217]
	v_mfma_f32_16x16x32_bf16 v[72:75], v[20:23], v[248:251], v[64:67]
	s_setprio 0
	s_setprio 1
	v_mfma_f32_16x16x32_bf16 v[64:67], v[152:155], v[24:27], v[96:99]
	v_mfma_f32_16x16x32_bf16 v[24:27], v[186:189], v[24:27], v[32:35]
	v_mfma_f32_16x16x32_bf16 v[132:135], v[194:197], v[28:31], v[24:27]
	v_mfma_f32_16x16x32_bf16 v[24:27], v[152:155], v[60:63], v[36:39]
	v_mfma_f32_16x16x32_bf16 v[104:107], v[156:159], v[100:103], v[24:27]
	v_mfma_f32_16x16x32_bf16 v[24:27], v[186:189], v[60:63], v[40:43]
	v_mfma_f32_16x16x32_bf16 v[100:103], v[194:197], v[100:103], v[24:27]
	v_mfma_f32_16x16x32_bf16 v[24:27], v[152:155], v[198:201], v[44:47]
	v_mfma_f32_16x16x32_bf16 v[84:87], v[156:159], v[234:237], v[24:27]
	v_mfma_f32_16x16x32_bf16 v[24:27], v[186:189], v[198:201], v[48:51]
	v_mfma_f32_16x16x32_bf16 v[80:83], v[194:197], v[234:237], v[24:27]
	v_mfma_f32_16x16x32_bf16 v[24:27], v[152:155], v[238:241], v[52:55]
	v_mfma_f32_16x16x32_bf16 v[68:71], v[156:159], v[248:251], v[24:27]
	v_mfma_f32_16x16x32_bf16 v[24:27], v[186:189], v[238:241], v[56:59]
	v_mfma_f32_16x16x32_bf16 v[140:143], v[156:159], v[28:31], v[64:67]
	v_mfma_f32_16x16x32_bf16 v[64:67], v[194:197], v[248:251], v[24:27]
	s_setprio 0
	s_barrier
	s_mov_b32 m0, s75
	s_nop 2
	v_lshl_add_u64 v[24:25], v[174:175], 0, s[82:83]
	s_add_u32 s4, s54, 0x10080
	ds_read_b128 v[32:35], v193 offset:49152
	ds_read_b128 v[36:39], v193 offset:50176
	ds_read_b128 v[96:99], v193 offset:51200
	ds_read_b128 v[198:201], v193 offset:52224
	ds_read_b128 v[210:213], v193 offset:53248
	ds_read_b128 v[214:217], v193 offset:54272
	ds_read_b128 v[234:237], v193 offset:55296
	ds_read_b128 v[238:241], v193 offset:56320
	global_load_lds_dwordx4 v[24:25], off
	v_lshl_add_u64 v[24:25], v[182:183], 0, s[82:83]
	s_mov_b32 m0, s73
	s_addc_u32 s5, s55, 0
	global_load_lds_dwordx4 v[24:25], off
	s_mov_b32 m0, s0
	s_nop 0
	global_load_lds_dwordx4 v176, s[4:5]
	s_mov_b32 m0, s1
	s_nop 0
	global_load_lds_dwordx4 v160, s[4:5]
	v_lshl_add_u64 v[24:25], v[190:191], 0, s[82:83]
	s_mov_b32 m0, s68
	s_nop 0
	global_load_lds_dwordx4 v[24:25], off
	v_lshl_add_u64 v[24:25], v[242:243], 0, s[82:83]
	s_mov_b32 m0, s69
	s_nop 0
	global_load_lds_dwordx4 v[24:25], off
	s_waitcnt vmcnt(8)
	s_waitcnt lgkmcnt(0)
	s_barrier
	s_setprio 1
	s_waitcnt lgkmcnt(0)
	v_mfma_f32_16x16x32_bf16 v[24:27], v[8:11], v[32:35], v[128:131]
	v_mfma_f32_16x16x32_bf16 v[60:63], v[12:15], v[36:39], v[24:27]
	v_mfma_f32_16x16x32_bf16 v[24:27], v[16:19], v[32:35], v[202:205]
	v_mfma_f32_16x16x32_bf16 v[56:59], v[20:23], v[36:39], v[24:27]
	v_mfma_f32_16x16x32_bf16 v[24:27], v[8:11], v[96:99], v[136:139]
	v_mfma_f32_16x16x32_bf16 v[44:47], v[12:15], v[198:201], v[24:27]
	v_mfma_f32_16x16x32_bf16 v[24:27], v[16:19], v[96:99], v[206:209]
	v_mfma_f32_16x16x32_bf16 v[40:43], v[20:23], v[198:201], v[24:27]
	v_mfma_f32_16x16x32_bf16 v[24:27], v[8:11], v[210:213], v[218:221]
	v_mfma_f32_16x16x32_bf16 v[0:3], v[8:11], v[234:237], v[0:3]
	v_mfma_f32_16x16x32_bf16 v[28:31], v[12:15], v[214:217], v[24:27]
	v_mfma_f32_16x16x32_bf16 v[24:27], v[16:19], v[210:213], v[222:225]
	v_mfma_f32_16x16x32_bf16 v[12:15], v[12:15], v[238:241], v[0:3]
	v_mfma_f32_16x16x32_bf16 v[0:3], v[16:19], v[234:237], v[4:7]
	v_mfma_f32_16x16x32_bf16 v[24:27], v[20:23], v[214:217], v[24:27]
	v_mfma_f32_16x16x32_bf16 v[8:11], v[20:23], v[238:241], v[0:3]
	s_setprio 0
	s_setprio 1
	v_mfma_f32_16x16x32_bf16 v[0:3], v[152:155], v[32:35], v[108:111]
	v_mfma_f32_16x16x32_bf16 v[52:55], v[156:159], v[36:39], v[0:3]
	v_mfma_f32_16x16x32_bf16 v[0:3], v[186:189], v[32:35], v[226:229]
	v_mfma_f32_16x16x32_bf16 v[48:51], v[194:197], v[36:39], v[0:3]
	v_mfma_f32_16x16x32_bf16 v[0:3], v[152:155], v[96:99], v[230:233]
	v_mfma_f32_16x16x32_bf16 v[36:39], v[156:159], v[198:201], v[0:3]
	v_mfma_f32_16x16x32_bf16 v[0:3], v[186:189], v[96:99], v[166:169]
	v_mfma_f32_16x16x32_bf16 v[32:35], v[194:197], v[198:201], v[0:3]
	v_mfma_f32_16x16x32_bf16 v[0:3], v[152:155], v[210:213], v[170:173]
	v_mfma_f32_16x16x32_bf16 v[20:23], v[156:159], v[214:217], v[0:3]
	v_mfma_f32_16x16x32_bf16 v[0:3], v[186:189], v[210:213], v[178:181]
	v_mfma_f32_16x16x32_bf16 v[16:19], v[194:197], v[214:217], v[0:3]
	v_mfma_f32_16x16x32_bf16 v[0:3], v[152:155], v[234:237], v[120:123]
	v_mfma_f32_16x16x32_bf16 v[4:7], v[156:159], v[238:241], v[0:3]
	v_mfma_f32_16x16x32_bf16 v[0:3], v[186:189], v[234:237], v[124:127]
	v_mfma_f32_16x16x32_bf16 v[0:3], v[194:197], v[238:241], v[0:3]
	s_setprio 0
	s_barrier
	s_andn2_b64 vcc, exec, s[38:39]
	s_cbranch_vccnz .LBB0_591
	s_barrier

.LBB0_662:
	s_add_u32 s0, s44, 0xfffc0080
	s_addc_u32 s1, s45, -1
	s_add_i32 s87, 0, 0x10000
	s_cmp_eq_u32 s86, 12
	s_cselect_b32 s5, s6, s1
	s_cselect_b32 s4, s7, s0
	s_cselect_b32 s1, s41, s75
	s_cselect_b32 s0, s53, s74
	s_add_i32 s90, 0, 0x14000
	v_add_u32_e32 v140, s87, v162
	v_add_u32_e32 v168, s90, v162
	ds_read_b128 v[128:131], v140
	ds_read_b128 v[132:135], v140 offset:1024
	ds_read_b128 v[136:139], v140 offset:2048
	ds_read_b128 v[140:143], v140 offset:3072
	ds_read_b128 v[154:157], v168
	ds_read_b128 v[158:161], v168 offset:1024
	ds_read_b128 v[164:167], v168 offset:2048
	ds_read_b128 v[168:171], v168 offset:3072
	s_add_i32 m0, s62, 0xc000
	ds_read_b128 v[172:175], v163
	ds_read_b128 v[178:181], v163 offset:1024
	ds_read_b128 v[186:189], v163 offset:2048
	ds_read_b128 v[190:193], v163 offset:3072
	ds_read_b128 v[194:197], v163 offset:4096
	ds_read_b128 v[198:201], v163 offset:5120
	ds_read_b128 v[202:205], v163 offset:6144
	ds_read_b128 v[206:209], v163 offset:7168
	global_load_lds_dwordx4 v150, s[44:45]
	s_add_i32 m0, s62, 0xe000
	s_nop 0
	global_load_lds_dwordx4 v152, s[44:45]
	s_waitcnt vmcnt(8)
	s_waitcnt lgkmcnt(0)
	s_barrier
	s_setprio 1
	s_waitcnt lgkmcnt(0)
	v_mfma_f32_16x16x32_bf16 v[124:127], v[128:131], v[172:175], v[124:127]
	v_mfma_f32_16x16x32_bf16 v[120:123], v[136:139], v[172:175], v[120:123]
	v_mfma_f32_16x16x32_bf16 v[108:111], v[128:131], v[186:189], v[108:111]
	v_mfma_f32_16x16x32_bf16 v[104:107], v[136:139], v[186:189], v[104:107]
	v_mfma_f32_16x16x32_bf16 v[92:95], v[128:131], v[194:197], v[92:95]
	v_mfma_f32_16x16x32_bf16 v[88:91], v[136:139], v[194:197], v[88:91]
	v_mfma_f32_16x16x32_bf16 v[76:79], v[128:131], v[202:205], v[76:79]
	v_mfma_f32_16x16x32_bf16 v[72:75], v[136:139], v[202:205], v[72:75]
	v_mfma_f32_16x16x32_bf16 v[124:127], v[132:135], v[178:181], v[124:127]
	v_mfma_f32_16x16x32_bf16 v[120:123], v[140:143], v[178:181], v[120:123]
	v_mfma_f32_16x16x32_bf16 v[108:111], v[132:135], v[190:193], v[108:111]
	v_mfma_f32_16x16x32_bf16 v[104:107], v[140:143], v[190:193], v[104:107]
	v_mfma_f32_16x16x32_bf16 v[92:95], v[132:135], v[198:201], v[92:95]
	v_mfma_f32_16x16x32_bf16 v[88:91], v[140:143], v[198:201], v[88:91]
	v_mfma_f32_16x16x32_bf16 v[76:79], v[132:135], v[206:209], v[76:79]
	v_mfma_f32_16x16x32_bf16 v[72:75], v[140:143], v[206:209], v[72:75]
	s_setprio 0
	s_setprio 1
	v_mfma_f32_16x16x32_bf16 v[116:119], v[154:157], v[172:175], v[116:119]
	v_mfma_f32_16x16x32_bf16 v[112:115], v[164:167], v[172:175], v[112:115]
	v_mfma_f32_16x16x32_bf16 v[100:103], v[154:157], v[186:189], v[100:103]
	v_mfma_f32_16x16x32_bf16 v[96:99], v[164:167], v[186:189], v[96:99]
	v_mfma_f32_16x16x32_bf16 v[84:87], v[154:157], v[194:197], v[84:87]
	v_mfma_f32_16x16x32_bf16 v[80:83], v[164:167], v[194:197], v[80:83]
	v_mfma_f32_16x16x32_bf16 v[68:71], v[154:157], v[202:205], v[68:71]
	v_mfma_f32_16x16x32_bf16 v[64:67], v[164:167], v[202:205], v[64:67]
	v_mfma_f32_16x16x32_bf16 v[116:119], v[158:161], v[178:181], v[116:119]
	v_mfma_f32_16x16x32_bf16 v[112:115], v[168:171], v[178:181], v[112:115]
	v_mfma_f32_16x16x32_bf16 v[100:103], v[158:161], v[190:193], v[100:103]
	v_mfma_f32_16x16x32_bf16 v[96:99], v[168:171], v[190:193], v[96:99]
	v_mfma_f32_16x16x32_bf16 v[84:87], v[158:161], v[198:201], v[84:87]
	v_mfma_f32_16x16x32_bf16 v[80:83], v[168:171], v[198:201], v[80:83]
	v_mfma_f32_16x16x32_bf16 v[68:71], v[158:161], v[206:209], v[68:71]
	v_mfma_f32_16x16x32_bf16 v[64:67], v[168:171], v[206:209], v[64:67]
	s_setprio 0
	s_barrier
	s_add_i32 s87, s87, s61
	v_lshl_add_u64 v[182:183], s[0:1], 0, v[176:177]
	s_mov_b32 m0, s87
	ds_read_b128 v[172:175], v163 offset:16384
	ds_read_b128 v[178:181], v163 offset:17408
	ds_read_b128 v[186:189], v163 offset:18432
	ds_read_b128 v[190:193], v163 offset:19456
	ds_read_b128 v[194:197], v163 offset:20480
	ds_read_b128 v[198:201], v163 offset:21504
	ds_read_b128 v[202:205], v163 offset:22528
	ds_read_b128 v[206:209], v163 offset:23552
	global_load_lds_dwordx4 v176, s[0:1]
	s_add_i32 m0, s87, 0x2000
	s_add_u32 s88, s0, 0x40000
	v_lshl_add_u64 v[210:211], s[0:1], 0, v[144:145]
	s_addc_u32 s89, s1, 0
	s_add_i32 s87, s90, s61
	global_load_lds_dwordx4 v144, s[0:1]
	s_mov_b32 m0, s87
	v_lshl_add_u64 v[214:215], s[4:5], 0, v[146:147]
	global_load_lds_dwordx4 v176, s[88:89]
	s_add_i32 m0, s87, 0x2000
	s_nop 0
	global_load_lds_dwordx4 v144, s[88:89]
	v_lshl_add_u64 v[212:213], s[4:5], 0, v[148:149]
	s_mov_b32 m0, s62
	s_nop 0
	global_load_lds_dwordx4 v148, s[4:5]
	s_mov_b32 m0, s63
	s_nop 0
	global_load_lds_dwordx4 v146, s[4:5]
	s_waitcnt vmcnt(8)
	s_waitcnt lgkmcnt(0)
	s_barrier
	s_setprio 1
	s_waitcnt lgkmcnt(0)
	v_mfma_f32_16x16x32_bf16 v[60:63], v[128:131], v[172:175], v[60:63]
	v_mfma_f32_16x16x32_bf16 v[56:59], v[136:139], v[172:175], v[56:59]
	v_mfma_f32_16x16x32_bf16 v[44:47], v[128:131], v[186:189], v[44:47]
	v_mfma_f32_16x16x32_bf16 v[40:43], v[136:139], v[186:189], v[40:43]
	v_mfma_f32_16x16x32_bf16 v[28:31], v[128:131], v[194:197], v[28:31]
	v_mfma_f32_16x16x32_bf16 v[24:27], v[136:139], v[194:197], v[24:27]
	v_mfma_f32_16x16x32_bf16 v[12:15], v[128:131], v[202:205], v[12:15]
	v_mfma_f32_16x16x32_bf16 v[8:11], v[136:139], v[202:205], v[8:11]
	v_mfma_f32_16x16x32_bf16 v[60:63], v[132:135], v[178:181], v[60:63]
	v_mfma_f32_16x16x32_bf16 v[56:59], v[140:143], v[178:181], v[56:59]
	v_mfma_f32_16x16x32_bf16 v[44:47], v[132:135], v[190:193], v[44:47]
	v_mfma_f32_16x16x32_bf16 v[40:43], v[140:143], v[190:193], v[40:43]
	v_mfma_f32_16x16x32_bf16 v[28:31], v[132:135], v[198:201], v[28:31]
	v_mfma_f32_16x16x32_bf16 v[24:27], v[140:143], v[198:201], v[24:27]
	v_mfma_f32_16x16x32_bf16 v[12:15], v[132:135], v[206:209], v[12:15]
	v_mfma_f32_16x16x32_bf16 v[8:11], v[140:143], v[206:209], v[8:11]
	s_setprio 0
	s_setprio 1
	v_mfma_f32_16x16x32_bf16 v[52:55], v[154:157], v[172:175], v[52:55]
	v_mfma_f32_16x16x32_bf16 v[48:51], v[164:167], v[172:175], v[48:51]
	v_mfma_f32_16x16x32_bf16 v[36:39], v[154:157], v[186:189], v[36:39]
	v_mfma_f32_16x16x32_bf16 v[32:35], v[164:167], v[186:189], v[32:35]
	v_mfma_f32_16x16x32_bf16 v[20:23], v[154:157], v[194:197], v[20:23]
	v_mfma_f32_16x16x32_bf16 v[16:19], v[164:167], v[194:197], v[16:19]
	v_mfma_f32_16x16x32_bf16 v[4:7], v[154:157], v[202:205], v[4:7]
	v_mfma_f32_16x16x32_bf16 v[0:3], v[164:167], v[202:205], v[0:3]
	v_mfma_f32_16x16x32_bf16 v[52:55], v[158:161], v[178:181], v[52:55]
	v_mfma_f32_16x16x32_bf16 v[48:51], v[168:171], v[178:181], v[48:51]
	v_mfma_f32_16x16x32_bf16 v[36:39], v[158:161], v[190:193], v[36:39]
	v_mfma_f32_16x16x32_bf16 v[32:35], v[168:171], v[190:193], v[32:35]
	v_mfma_f32_16x16x32_bf16 v[20:23], v[158:161], v[198:201], v[20:23]
	v_mfma_f32_16x16x32_bf16 v[16:19], v[168:171], v[198:201], v[16:19]
	v_mfma_f32_16x16x32_bf16 v[4:7], v[158:161], v[206:209], v[4:7]
	v_mfma_f32_16x16x32_bf16 v[0:3], v[168:171], v[206:209], v[0:3]
	s_setprio 0
	s_barrier
	s_add_i32 s87, 0, 0x18000
	s_add_i32 s88, 0, 0x1c000
	v_add_u32_e32 v140, s87, v162
	v_add_u32_e32 v168, s88, v162
	ds_read_b128 v[128:131], v140
	ds_read_b128 v[132:135], v140 offset:1024
	ds_read_b128 v[136:139], v140 offset:2048
	ds_read_b128 v[140:143], v140 offset:3072
	ds_read_b128 v[154:157], v168
	ds_read_b128 v[158:161], v168 offset:1024
	ds_read_b128 v[164:167], v168 offset:2048
	ds_read_b128 v[168:171], v168 offset:3072
	s_add_u32 s4, s4, 0x40000
	s_addc_u32 s5, s5, 0
	s_mov_b32 m0, s64
	ds_read_b128 v[172:175], v163 offset:32768
	ds_read_b128 v[178:181], v163 offset:33792
	ds_read_b128 v[186:189], v163 offset:34816
	ds_read_b128 v[190:193], v163 offset:35840
	ds_read_b128 v[194:197], v163 offset:36864
	ds_read_b128 v[198:201], v163 offset:37888
	ds_read_b128 v[202:205], v163 offset:38912
	ds_read_b128 v[206:209], v163 offset:39936
	global_load_lds_dwordx4 v148, s[4:5]
	s_mov_b32 m0, s65
	s_nop 0
	global_load_lds_dwordx4 v146, s[4:5]
	s_waitcnt vmcnt(8)
	s_waitcnt lgkmcnt(0)
	s_barrier
	s_setprio 1
	s_waitcnt lgkmcnt(0)
	v_mfma_f32_16x16x32_bf16 v[124:127], v[128:131], v[172:175], v[124:127]
	v_mfma_f32_16x16x32_bf16 v[120:123], v[136:139], v[172:175], v[120:123]
	v_mfma_f32_16x16x32_bf16 v[108:111], v[128:131], v[186:189], v[108:111]
	v_mfma_f32_16x16x32_bf16 v[104:107], v[136:139], v[186:189], v[104:107]
	v_mfma_f32_16x16x32_bf16 v[92:95], v[128:131], v[194:197], v[92:95]
	v_mfma_f32_16x16x32_bf16 v[88:91], v[136:139], v[194:197], v[88:91]
	v_mfma_f32_16x16x32_bf16 v[76:79], v[128:131], v[202:205], v[76:79]
	v_mfma_f32_16x16x32_bf16 v[72:75], v[136:139], v[202:205], v[72:75]
	v_mfma_f32_16x16x32_bf16 v[124:127], v[132:135], v[178:181], v[124:127]
	v_mfma_f32_16x16x32_bf16 v[120:123], v[140:143], v[178:181], v[120:123]
	v_mfma_f32_16x16x32_bf16 v[108:111], v[132:135], v[190:193], v[108:111]
	v_mfma_f32_16x16x32_bf16 v[104:107], v[140:143], v[190:193], v[104:107]
	v_mfma_f32_16x16x32_bf16 v[92:95], v[132:135], v[198:201], v[92:95]
	v_mfma_f32_16x16x32_bf16 v[88:91], v[140:143], v[198:201], v[88:91]
	v_mfma_f32_16x16x32_bf16 v[76:79], v[132:135], v[206:209], v[76:79]
	v_mfma_f32_16x16x32_bf16 v[72:75], v[140:143], v[206:209], v[72:75]
	s_setprio 0
	s_setprio 1
	v_mfma_f32_16x16x32_bf16 v[116:119], v[154:157], v[172:175], v[116:119]
	v_mfma_f32_16x16x32_bf16 v[112:115], v[164:167], v[172:175], v[112:115]
	v_mfma_f32_16x16x32_bf16 v[100:103], v[154:157], v[186:189], v[100:103]
	v_mfma_f32_16x16x32_bf16 v[96:99], v[164:167], v[186:189], v[96:99]
	v_mfma_f32_16x16x32_bf16 v[84:87], v[154:157], v[194:197], v[84:87]
	v_mfma_f32_16x16x32_bf16 v[80:83], v[164:167], v[194:197], v[80:83]
	v_mfma_f32_16x16x32_bf16 v[68:71], v[154:157], v[202:205], v[68:71]
	v_mfma_f32_16x16x32_bf16 v[64:67], v[164:167], v[202:205], v[64:67]
	v_mfma_f32_16x16x32_bf16 v[116:119], v[158:161], v[178:181], v[116:119]
	v_mfma_f32_16x16x32_bf16 v[112:115], v[168:171], v[178:181], v[112:115]
	v_mfma_f32_16x16x32_bf16 v[100:103], v[158:161], v[190:193], v[100:103]
	v_mfma_f32_16x16x32_bf16 v[96:99], v[168:171], v[190:193], v[96:99]
	v_mfma_f32_16x16x32_bf16 v[84:87], v[158:161], v[198:201], v[84:87]
	v_mfma_f32_16x16x32_bf16 v[80:83], v[168:171], v[198:201], v[80:83]
	v_mfma_f32_16x16x32_bf16 v[68:71], v[158:161], v[206:209], v[68:71]
	v_mfma_f32_16x16x32_bf16 v[64:67], v[168:171], v[206:209], v[64:67]
	s_setprio 0
	s_barrier
	s_add_i32 s4, s87, s61
	v_lshl_add_u64 v[182:183], v[182:183], 0, s[82:83]
	s_mov_b32 m0, s4
	ds_read_b128 v[172:175], v163 offset:49152
	ds_read_b128 v[178:181], v163 offset:50176
	ds_read_b128 v[186:189], v163 offset:51200
	ds_read_b128 v[190:193], v163 offset:52224
	ds_read_b128 v[194:197], v163 offset:53248
	ds_read_b128 v[198:201], v163 offset:54272
	ds_read_b128 v[202:205], v163 offset:55296
	ds_read_b128 v[206:209], v163 offset:56320
	global_load_lds_dwordx4 v[182:183], off
	s_add_i32 m0, s4, 0x2000
	s_add_u32 s0, s0, 0x40080
	v_lshl_add_u64 v[182:183], v[210:211], 0, s[82:83]
	s_addc_u32 s1, s1, 0
	s_add_i32 s4, s88, s61
	global_load_lds_dwordx4 v[182:183], off
	s_mov_b32 m0, s4
	s_nop 0
	global_load_lds_dwordx4 v176, s[0:1]
	s_add_i32 m0, s4, 0x2000
	s_nop 0
	global_load_lds_dwordx4 v144, s[0:1]
	v_lshl_add_u64 v[182:183], v[212:213], 0, s[82:83]
	s_mov_b32 m0, s69
	s_nop 0
	global_load_lds_dwordx4 v[182:183], off
	v_lshl_add_u64 v[182:183], v[214:215], 0, s[82:83]
	s_mov_b32 m0, s70
	s_nop 0
	global_load_lds_dwordx4 v[182:183], off
	s_waitcnt vmcnt(8)
	s_waitcnt lgkmcnt(0)
	s_barrier
	s_setprio 1
	s_waitcnt lgkmcnt(0)
	v_mfma_f32_16x16x32_bf16 v[60:63], v[128:131], v[172:175], v[60:63]
	v_mfma_f32_16x16x32_bf16 v[56:59], v[136:139], v[172:175], v[56:59]
	v_mfma_f32_16x16x32_bf16 v[44:47], v[128:131], v[186:189], v[44:47]
	v_mfma_f32_16x16x32_bf16 v[40:43], v[136:139], v[186:189], v[40:43]
	v_mfma_f32_16x16x32_bf16 v[28:31], v[128:131], v[194:197], v[28:31]
	v_mfma_f32_16x16x32_bf16 v[24:27], v[136:139], v[194:197], v[24:27]
	v_mfma_f32_16x16x32_bf16 v[12:15], v[128:131], v[202:205], v[12:15]
	v_mfma_f32_16x16x32_bf16 v[8:11], v[136:139], v[202:205], v[8:11]
	v_mfma_f32_16x16x32_bf16 v[60:63], v[132:135], v[178:181], v[60:63]
	v_mfma_f32_16x16x32_bf16 v[56:59], v[140:143], v[178:181], v[56:59]
	v_mfma_f32_16x16x32_bf16 v[44:47], v[132:135], v[190:193], v[44:47]
	v_mfma_f32_16x16x32_bf16 v[40:43], v[140:143], v[190:193], v[40:43]
	v_mfma_f32_16x16x32_bf16 v[28:31], v[132:135], v[198:201], v[28:31]
	v_mfma_f32_16x16x32_bf16 v[24:27], v[140:143], v[198:201], v[24:27]
	v_mfma_f32_16x16x32_bf16 v[12:15], v[132:135], v[206:209], v[12:15]
	v_mfma_f32_16x16x32_bf16 v[8:11], v[140:143], v[206:209], v[8:11]
	s_setprio 0
	s_setprio 1
	v_mfma_f32_16x16x32_bf16 v[52:55], v[154:157], v[172:175], v[52:55]
	v_mfma_f32_16x16x32_bf16 v[48:51], v[164:167], v[172:175], v[48:51]
	v_mfma_f32_16x16x32_bf16 v[36:39], v[154:157], v[186:189], v[36:39]
	v_mfma_f32_16x16x32_bf16 v[32:35], v[164:167], v[186:189], v[32:35]
	v_mfma_f32_16x16x32_bf16 v[20:23], v[154:157], v[194:197], v[20:23]
	v_mfma_f32_16x16x32_bf16 v[16:19], v[164:167], v[194:197], v[16:19]
	v_mfma_f32_16x16x32_bf16 v[4:7], v[154:157], v[202:205], v[4:7]
	v_mfma_f32_16x16x32_bf16 v[0:3], v[164:167], v[202:205], v[0:3]
	v_mfma_f32_16x16x32_bf16 v[52:55], v[158:161], v[178:181], v[52:55]
	v_mfma_f32_16x16x32_bf16 v[48:51], v[168:171], v[178:181], v[48:51]
	v_mfma_f32_16x16x32_bf16 v[36:39], v[158:161], v[190:193], v[36:39]
	v_mfma_f32_16x16x32_bf16 v[32:35], v[168:171], v[190:193], v[32:35]
	v_mfma_f32_16x16x32_bf16 v[20:23], v[158:161], v[198:201], v[20:23]
	v_mfma_f32_16x16x32_bf16 v[16:19], v[168:171], v[198:201], v[16:19]
	v_mfma_f32_16x16x32_bf16 v[4:7], v[158:161], v[206:209], v[4:7]
	v_mfma_f32_16x16x32_bf16 v[0:3], v[168:171], v[206:209], v[0:3]
	s_setprio 0
	s_barrier
	s_add_i32 s86, s86, 2
	s_add_u32 s44, s44, 0x100
	s_addc_u32 s45, s45, 0
	s_add_u32 s74, s74, 0x100
	s_addc_u32 s75, s75, 0
	s_cmp_gt_u32 s86, 13
	s_cbranch_scc0 .LBB0_662
	s_and_b64 vcc, exec, s[38:39]
	s_cbranch_vccz .LBB0_665
	s_barrier

.LBB0_748:
	s_add_u32 s0, s44, 0xfffc0080
	s_addc_u32 s1, s45, -1
	s_add_i32 s74, 0, 0x10000
	s_cmp_eq_u32 s73, 12
	s_cselect_b32 s5, s6, s1
	s_cselect_b32 s4, s7, s0
	s_cselect_b32 s1, s39, s72
	s_cselect_b32 s0, s41, s49
	s_add_i32 s92, 0, 0x14000
	v_add_u32_e32 v124, s74, v199
	v_add_u32_e32 v140, s92, v199
	ds_read_b128 v[112:115], v124
	ds_read_b128 v[116:119], v124 offset:1024
	ds_read_b128 v[120:123], v124 offset:2048
	ds_read_b128 v[124:127], v124 offset:3072
	ds_read_b128 v[128:131], v140
	ds_read_b128 v[132:135], v140 offset:1024
	ds_read_b128 v[136:139], v140 offset:2048
	ds_read_b128 v[140:143], v140 offset:3072
	s_add_i32 m0, s63, 0xc000
	ds_read_b128 v[172:175], v207
	ds_read_b128 v[178:181], v207 offset:1024
	ds_read_b128 v[186:189], v207 offset:2048
	ds_read_b128 v[190:193], v207 offset:3072
	ds_read_b128 v[194:197], v207 offset:4096
	ds_read_b128 v[200:203], v207 offset:5120
	ds_read_b128 v[208:211], v207 offset:6144
	ds_read_b128 v[212:215], v207 offset:7168
	global_load_lds_dwordx4 v168, s[44:45]
	s_add_i32 m0, s63, 0xe000
	s_nop 0
	global_load_lds_dwordx4 v170, s[44:45]
	s_waitcnt vmcnt(8)
	s_waitcnt lgkmcnt(0)
	s_barrier
	s_setprio 1
	s_waitcnt lgkmcnt(0)
	v_mfma_f32_16x16x32_bf16 v[156:159], v[112:115], v[172:175], v[156:159]
	v_mfma_f32_16x16x32_bf16 v[152:155], v[120:123], v[172:175], v[152:155]
	v_mfma_f32_16x16x32_bf16 v[108:111], v[112:115], v[186:189], v[108:111]
	v_mfma_f32_16x16x32_bf16 v[100:103], v[120:123], v[186:189], v[100:103]
	v_mfma_f32_16x16x32_bf16 v[92:95], v[112:115], v[194:197], v[92:95]
	v_mfma_f32_16x16x32_bf16 v[84:87], v[120:123], v[194:197], v[84:87]
	v_mfma_f32_16x16x32_bf16 v[76:79], v[112:115], v[208:211], v[76:79]
	v_mfma_f32_16x16x32_bf16 v[68:71], v[120:123], v[208:211], v[68:71]
	v_mfma_f32_16x16x32_bf16 v[156:159], v[116:119], v[178:181], v[156:159]
	v_mfma_f32_16x16x32_bf16 v[152:155], v[124:127], v[178:181], v[152:155]
	v_mfma_f32_16x16x32_bf16 v[108:111], v[116:119], v[190:193], v[108:111]
	v_mfma_f32_16x16x32_bf16 v[100:103], v[124:127], v[190:193], v[100:103]
	v_mfma_f32_16x16x32_bf16 v[92:95], v[116:119], v[200:203], v[92:95]
	v_mfma_f32_16x16x32_bf16 v[84:87], v[124:127], v[200:203], v[84:87]
	v_mfma_f32_16x16x32_bf16 v[76:79], v[116:119], v[212:215], v[76:79]
	v_mfma_f32_16x16x32_bf16 v[68:71], v[124:127], v[212:215], v[68:71]
	s_setprio 0
	s_setprio 1
	v_mfma_f32_16x16x32_bf16 v[148:151], v[128:131], v[172:175], v[148:151]
	v_mfma_f32_16x16x32_bf16 v[144:147], v[136:139], v[172:175], v[144:147]
	v_mfma_f32_16x16x32_bf16 v[104:107], v[128:131], v[186:189], v[104:107]
	v_mfma_f32_16x16x32_bf16 v[96:99], v[136:139], v[186:189], v[96:99]
	v_mfma_f32_16x16x32_bf16 v[88:91], v[128:131], v[194:197], v[88:91]
	v_mfma_f32_16x16x32_bf16 v[80:83], v[136:139], v[194:197], v[80:83]
	v_mfma_f32_16x16x32_bf16 v[72:75], v[128:131], v[208:211], v[72:75]
	v_mfma_f32_16x16x32_bf16 v[64:67], v[136:139], v[208:211], v[64:67]
	v_mfma_f32_16x16x32_bf16 v[148:151], v[132:135], v[178:181], v[148:151]
	v_mfma_f32_16x16x32_bf16 v[144:147], v[140:143], v[178:181], v[144:147]
	v_mfma_f32_16x16x32_bf16 v[104:107], v[132:135], v[190:193], v[104:107]
	v_mfma_f32_16x16x32_bf16 v[96:99], v[140:143], v[190:193], v[96:99]
	v_mfma_f32_16x16x32_bf16 v[88:91], v[132:135], v[200:203], v[88:91]
	v_mfma_f32_16x16x32_bf16 v[80:83], v[140:143], v[200:203], v[80:83]
	v_mfma_f32_16x16x32_bf16 v[72:75], v[132:135], v[212:215], v[72:75]
	v_mfma_f32_16x16x32_bf16 v[64:67], v[140:143], v[212:215], v[64:67]
	s_setprio 0
	s_barrier
	s_add_i32 s74, s74, s62
	v_lshl_add_u64 v[182:183], s[0:1], 0, v[164:165]
	s_mov_b32 m0, s74
	ds_read_b128 v[172:175], v207 offset:16384
	ds_read_b128 v[178:181], v207 offset:17408
	ds_read_b128 v[186:189], v207 offset:18432
	ds_read_b128 v[190:193], v207 offset:19456
	ds_read_b128 v[194:197], v207 offset:20480
	ds_read_b128 v[200:203], v207 offset:21504
	ds_read_b128 v[208:211], v207 offset:22528
	ds_read_b128 v[212:215], v207 offset:23552
	global_load_lds_dwordx4 v164, s[0:1]
	s_add_i32 m0, s74, 0x2000
	s_add_u32 s74, s0, 0x40000
	v_lshl_add_u64 v[204:205], s[0:1], 0, v[160:161]
	s_addc_u32 s75, s1, 0
	s_add_i32 s92, s92, s62
	global_load_lds_dwordx4 v160, s[0:1]
	s_mov_b32 m0, s92
	v_lshl_add_u64 v[218:219], s[4:5], 0, v[162:163]
	global_load_lds_dwordx4 v164, s[74:75]
	s_add_i32 m0, s92, 0x2000
	s_nop 0
	global_load_lds_dwordx4 v160, s[74:75]
	v_lshl_add_u64 v[216:217], s[4:5], 0, v[166:167]
	s_mov_b32 m0, s63
	s_nop 0
	global_load_lds_dwordx4 v166, s[4:5]
	s_mov_b32 m0, s64
	s_nop 0
	global_load_lds_dwordx4 v162, s[4:5]
	s_waitcnt vmcnt(8)
	s_waitcnt lgkmcnt(0)
	s_barrier
	s_setprio 1
	s_waitcnt lgkmcnt(0)
	v_mfma_f32_16x16x32_bf16 v[60:63], v[112:115], v[172:175], v[60:63]
	v_mfma_f32_16x16x32_bf16 v[56:59], v[120:123], v[172:175], v[56:59]
	v_mfma_f32_16x16x32_bf16 v[44:47], v[112:115], v[186:189], v[44:47]
	v_mfma_f32_16x16x32_bf16 v[36:39], v[120:123], v[186:189], v[36:39]
	v_mfma_f32_16x16x32_bf16 v[28:31], v[112:115], v[194:197], v[28:31]
	v_mfma_f32_16x16x32_bf16 v[20:23], v[120:123], v[194:197], v[20:23]
	v_mfma_f32_16x16x32_bf16 v[12:15], v[112:115], v[208:211], v[12:15]
	v_mfma_f32_16x16x32_bf16 v[4:7], v[120:123], v[208:211], v[4:7]
	v_mfma_f32_16x16x32_bf16 v[60:63], v[116:119], v[178:181], v[60:63]
	v_mfma_f32_16x16x32_bf16 v[56:59], v[124:127], v[178:181], v[56:59]
	v_mfma_f32_16x16x32_bf16 v[44:47], v[116:119], v[190:193], v[44:47]
	v_mfma_f32_16x16x32_bf16 v[36:39], v[124:127], v[190:193], v[36:39]
	v_mfma_f32_16x16x32_bf16 v[28:31], v[116:119], v[200:203], v[28:31]
	v_mfma_f32_16x16x32_bf16 v[20:23], v[124:127], v[200:203], v[20:23]
	v_mfma_f32_16x16x32_bf16 v[12:15], v[116:119], v[212:215], v[12:15]
	v_mfma_f32_16x16x32_bf16 v[4:7], v[124:127], v[212:215], v[4:7]
	s_setprio 0
	s_setprio 1
	v_mfma_f32_16x16x32_bf16 v[52:55], v[128:131], v[172:175], v[52:55]
	v_mfma_f32_16x16x32_bf16 v[48:51], v[136:139], v[172:175], v[48:51]
	v_mfma_f32_16x16x32_bf16 v[40:43], v[128:131], v[186:189], v[40:43]
	v_mfma_f32_16x16x32_bf16 v[32:35], v[136:139], v[186:189], v[32:35]
	v_mfma_f32_16x16x32_bf16 v[24:27], v[128:131], v[194:197], v[24:27]
	v_mfma_f32_16x16x32_bf16 v[16:19], v[136:139], v[194:197], v[16:19]
	v_mfma_f32_16x16x32_bf16 v[8:11], v[128:131], v[208:211], v[8:11]
	v_mfma_f32_16x16x32_bf16 v[0:3], v[136:139], v[208:211], v[0:3]
	v_mfma_f32_16x16x32_bf16 v[52:55], v[132:135], v[178:181], v[52:55]
	v_mfma_f32_16x16x32_bf16 v[48:51], v[140:143], v[178:181], v[48:51]
	v_mfma_f32_16x16x32_bf16 v[40:43], v[132:135], v[190:193], v[40:43]
	v_mfma_f32_16x16x32_bf16 v[32:35], v[140:143], v[190:193], v[32:35]
	v_mfma_f32_16x16x32_bf16 v[24:27], v[132:135], v[200:203], v[24:27]
	v_mfma_f32_16x16x32_bf16 v[16:19], v[140:143], v[200:203], v[16:19]
	v_mfma_f32_16x16x32_bf16 v[8:11], v[132:135], v[212:215], v[8:11]
	v_mfma_f32_16x16x32_bf16 v[0:3], v[140:143], v[212:215], v[0:3]
	s_setprio 0
	s_barrier
	s_add_i32 s74, 0, 0x18000
	s_add_i32 s75, 0, 0x1c000
	v_add_u32_e32 v124, s74, v199
	v_add_u32_e32 v140, s75, v199
	ds_read_b128 v[112:115], v124
	ds_read_b128 v[116:119], v124 offset:1024
	ds_read_b128 v[120:123], v124 offset:2048
	ds_read_b128 v[124:127], v124 offset:3072
	ds_read_b128 v[128:131], v140
	ds_read_b128 v[132:135], v140 offset:1024
	ds_read_b128 v[136:139], v140 offset:2048
	ds_read_b128 v[140:143], v140 offset:3072
	s_add_u32 s4, s4, 0x40000
	s_addc_u32 s5, s5, 0
	s_mov_b32 m0, s65
	ds_read_b128 v[172:175], v207 offset:32768
	ds_read_b128 v[178:181], v207 offset:33792
	ds_read_b128 v[186:189], v207 offset:34816
	ds_read_b128 v[190:193], v207 offset:35840
	ds_read_b128 v[194:197], v207 offset:36864
	ds_read_b128 v[200:203], v207 offset:37888
	ds_read_b128 v[208:211], v207 offset:38912
	ds_read_b128 v[212:215], v207 offset:39936
	global_load_lds_dwordx4 v166, s[4:5]
	s_mov_b32 m0, s66
	s_nop 0
	global_load_lds_dwordx4 v162, s[4:5]
	s_waitcnt vmcnt(8)
	s_waitcnt lgkmcnt(0)
	s_barrier
	s_setprio 1
	s_waitcnt lgkmcnt(0)
	v_mfma_f32_16x16x32_bf16 v[156:159], v[112:115], v[172:175], v[156:159]
	v_mfma_f32_16x16x32_bf16 v[152:155], v[120:123], v[172:175], v[152:155]
	v_mfma_f32_16x16x32_bf16 v[108:111], v[112:115], v[186:189], v[108:111]
	v_mfma_f32_16x16x32_bf16 v[100:103], v[120:123], v[186:189], v[100:103]
	v_mfma_f32_16x16x32_bf16 v[92:95], v[112:115], v[194:197], v[92:95]
	v_mfma_f32_16x16x32_bf16 v[84:87], v[120:123], v[194:197], v[84:87]
	v_mfma_f32_16x16x32_bf16 v[76:79], v[112:115], v[208:211], v[76:79]
	v_mfma_f32_16x16x32_bf16 v[68:71], v[120:123], v[208:211], v[68:71]
	v_mfma_f32_16x16x32_bf16 v[156:159], v[116:119], v[178:181], v[156:159]
	v_mfma_f32_16x16x32_bf16 v[152:155], v[124:127], v[178:181], v[152:155]
	v_mfma_f32_16x16x32_bf16 v[108:111], v[116:119], v[190:193], v[108:111]
	v_mfma_f32_16x16x32_bf16 v[100:103], v[124:127], v[190:193], v[100:103]
	v_mfma_f32_16x16x32_bf16 v[92:95], v[116:119], v[200:203], v[92:95]
	v_mfma_f32_16x16x32_bf16 v[84:87], v[124:127], v[200:203], v[84:87]
	v_mfma_f32_16x16x32_bf16 v[76:79], v[116:119], v[212:215], v[76:79]
	v_mfma_f32_16x16x32_bf16 v[68:71], v[124:127], v[212:215], v[68:71]
	s_setprio 0
	s_setprio 1
	v_mfma_f32_16x16x32_bf16 v[148:151], v[128:131], v[172:175], v[148:151]
	v_mfma_f32_16x16x32_bf16 v[144:147], v[136:139], v[172:175], v[144:147]
	v_mfma_f32_16x16x32_bf16 v[104:107], v[128:131], v[186:189], v[104:107]
	v_mfma_f32_16x16x32_bf16 v[96:99], v[136:139], v[186:189], v[96:99]
	v_mfma_f32_16x16x32_bf16 v[88:91], v[128:131], v[194:197], v[88:91]
	v_mfma_f32_16x16x32_bf16 v[80:83], v[136:139], v[194:197], v[80:83]
	v_mfma_f32_16x16x32_bf16 v[72:75], v[128:131], v[208:211], v[72:75]
	v_mfma_f32_16x16x32_bf16 v[64:67], v[136:139], v[208:211], v[64:67]
	v_mfma_f32_16x16x32_bf16 v[148:151], v[132:135], v[178:181], v[148:151]
	v_mfma_f32_16x16x32_bf16 v[144:147], v[140:143], v[178:181], v[144:147]
	v_mfma_f32_16x16x32_bf16 v[104:107], v[132:135], v[190:193], v[104:107]
	v_mfma_f32_16x16x32_bf16 v[96:99], v[140:143], v[190:193], v[96:99]
	v_mfma_f32_16x16x32_bf16 v[88:91], v[132:135], v[200:203], v[88:91]
	v_mfma_f32_16x16x32_bf16 v[80:83], v[140:143], v[200:203], v[80:83]
	v_mfma_f32_16x16x32_bf16 v[72:75], v[132:135], v[212:215], v[72:75]
	v_mfma_f32_16x16x32_bf16 v[64:67], v[140:143], v[212:215], v[64:67]
	s_setprio 0
	s_barrier
	s_add_i32 s4, s74, s62
	v_lshl_add_u64 v[182:183], v[182:183], 0, s[82:83]
	s_mov_b32 m0, s4
	ds_read_b128 v[172:175], v207 offset:49152
	ds_read_b128 v[178:181], v207 offset:50176
	ds_read_b128 v[186:189], v207 offset:51200
	ds_read_b128 v[190:193], v207 offset:52224
	ds_read_b128 v[194:197], v207 offset:53248
	ds_read_b128 v[200:203], v207 offset:54272
	ds_read_b128 v[208:211], v207 offset:55296
	ds_read_b128 v[212:215], v207 offset:56320
	global_load_lds_dwordx4 v[182:183], off
	s_add_i32 m0, s4, 0x2000
	s_add_u32 s0, s0, 0x40080
	v_lshl_add_u64 v[182:183], v[204:205], 0, s[82:83]
	s_addc_u32 s1, s1, 0
	s_add_i32 s4, s75, s62
	global_load_lds_dwordx4 v[182:183], off
	s_mov_b32 m0, s4
	s_nop 0
	global_load_lds_dwordx4 v164, s[0:1]
	s_add_i32 m0, s4, 0x2000
	s_nop 0
	global_load_lds_dwordx4 v160, s[0:1]
	v_lshl_add_u64 v[182:183], v[216:217], 0, s[82:83]
	s_mov_b32 m0, s69
	s_nop 0
	global_load_lds_dwordx4 v[182:183], off
	v_lshl_add_u64 v[182:183], v[218:219], 0, s[82:83]
	s_mov_b32 m0, s70
	s_nop 0
	global_load_lds_dwordx4 v[182:183], off
	s_waitcnt vmcnt(8)
	s_waitcnt lgkmcnt(0)
	s_barrier
	s_setprio 1
	s_waitcnt lgkmcnt(0)
	v_mfma_f32_16x16x32_bf16 v[60:63], v[112:115], v[172:175], v[60:63]
	v_mfma_f32_16x16x32_bf16 v[56:59], v[120:123], v[172:175], v[56:59]
	v_mfma_f32_16x16x32_bf16 v[44:47], v[112:115], v[186:189], v[44:47]
	v_mfma_f32_16x16x32_bf16 v[36:39], v[120:123], v[186:189], v[36:39]
	v_mfma_f32_16x16x32_bf16 v[28:31], v[112:115], v[194:197], v[28:31]
	v_mfma_f32_16x16x32_bf16 v[20:23], v[120:123], v[194:197], v[20:23]
	v_mfma_f32_16x16x32_bf16 v[12:15], v[112:115], v[208:211], v[12:15]
	v_mfma_f32_16x16x32_bf16 v[4:7], v[120:123], v[208:211], v[4:7]
	v_mfma_f32_16x16x32_bf16 v[60:63], v[116:119], v[178:181], v[60:63]
	v_mfma_f32_16x16x32_bf16 v[56:59], v[124:127], v[178:181], v[56:59]
	v_mfma_f32_16x16x32_bf16 v[44:47], v[116:119], v[190:193], v[44:47]
	v_mfma_f32_16x16x32_bf16 v[36:39], v[124:127], v[190:193], v[36:39]
	v_mfma_f32_16x16x32_bf16 v[28:31], v[116:119], v[200:203], v[28:31]
	v_mfma_f32_16x16x32_bf16 v[20:23], v[124:127], v[200:203], v[20:23]
	v_mfma_f32_16x16x32_bf16 v[12:15], v[116:119], v[212:215], v[12:15]
	v_mfma_f32_16x16x32_bf16 v[4:7], v[124:127], v[212:215], v[4:7]
	s_setprio 0
	s_setprio 1
	v_mfma_f32_16x16x32_bf16 v[52:55], v[128:131], v[172:175], v[52:55]
	v_mfma_f32_16x16x32_bf16 v[48:51], v[136:139], v[172:175], v[48:51]
	v_mfma_f32_16x16x32_bf16 v[40:43], v[128:131], v[186:189], v[40:43]
	v_mfma_f32_16x16x32_bf16 v[32:35], v[136:139], v[186:189], v[32:35]
	v_mfma_f32_16x16x32_bf16 v[24:27], v[128:131], v[194:197], v[24:27]
	v_mfma_f32_16x16x32_bf16 v[16:19], v[136:139], v[194:197], v[16:19]
	v_mfma_f32_16x16x32_bf16 v[8:11], v[128:131], v[208:211], v[8:11]
	v_mfma_f32_16x16x32_bf16 v[0:3], v[136:139], v[208:211], v[0:3]
	v_mfma_f32_16x16x32_bf16 v[52:55], v[132:135], v[178:181], v[52:55]
	v_mfma_f32_16x16x32_bf16 v[48:51], v[140:143], v[178:181], v[48:51]
	v_mfma_f32_16x16x32_bf16 v[40:43], v[132:135], v[190:193], v[40:43]
	v_mfma_f32_16x16x32_bf16 v[32:35], v[140:143], v[190:193], v[32:35]
	v_mfma_f32_16x16x32_bf16 v[24:27], v[132:135], v[200:203], v[24:27]
	v_mfma_f32_16x16x32_bf16 v[16:19], v[140:143], v[200:203], v[16:19]
	v_mfma_f32_16x16x32_bf16 v[8:11], v[132:135], v[212:215], v[8:11]
	v_mfma_f32_16x16x32_bf16 v[0:3], v[140:143], v[212:215], v[0:3]
	s_setprio 0
	s_barrier
	s_add_i32 s73, s73, 2
	s_add_u32 s44, s44, 0x100
	s_addc_u32 s45, s45, 0
	s_add_u32 s49, s49, 0x100
	s_addc_u32 s72, s72, 0
	s_cmp_gt_u32 s73, 13
	s_cbranch_scc0 .LBB0_748
	s_and_b64 vcc, exec, s[90:91]
	s_cbranch_vccz .LBB0_751
	s_barrier

.LBB0_930:
	s_add_u32 s0, s54, 0x100
	s_addc_u32 s1, s55, 0
	s_add_i32 s72, 0, 0x10000
	s_cmp_eq_u32 s71, 40
	s_cselect_b32 s43, s51, s1
	s_cselect_b32 s42, s50, s0
	s_cselect_b32 s5, s53, s70
	s_cselect_b32 s4, s52, s69
	s_add_i32 s73, 0, 0x14000
	v_add_u32_e32 v140, s72, v164
	v_add_u32_e32 v162, s73, v164
	ds_read_b128 v[128:131], v140
	ds_read_b128 v[132:135], v140 offset:1024
	ds_read_b128 v[136:139], v140 offset:2048
	ds_read_b128 v[140:143], v140 offset:3072
	ds_read_b128 v[154:157], v162
	ds_read_b128 v[158:161], v162 offset:1024
	ds_read_b128 v[166:169], v162 offset:2048
	ds_read_b128 v[170:173], v162 offset:3072
	s_add_i32 m0, s20, 0xc000
	ds_read_b128 v[178:181], v165
	ds_read_b128 v[186:189], v165 offset:1024
	ds_read_b128 v[190:193], v165 offset:2048
	ds_read_b128 v[194:197], v165 offset:3072
	ds_read_b128 v[198:201], v165 offset:4096
	ds_read_b128 v[202:205], v165 offset:5120
	ds_read_b128 v[206:209], v165 offset:6144
	ds_read_b128 v[210:213], v165 offset:7168
	global_load_lds_dwordx4 v150, s[54:55]
	s_add_i32 m0, s20, 0xe000
	s_nop 0
	global_load_lds_dwordx4 v152, s[54:55]
	s_waitcnt vmcnt(8)
	s_waitcnt lgkmcnt(0)
	s_barrier
	s_setprio 1
	s_waitcnt lgkmcnt(0)
	v_mfma_f32_16x16x32_bf16 v[124:127], v[128:131], v[178:181], v[124:127]
	v_mfma_f32_16x16x32_bf16 v[120:123], v[136:139], v[178:181], v[120:123]
	v_mfma_f32_16x16x32_bf16 v[108:111], v[128:131], v[190:193], v[108:111]
	v_mfma_f32_16x16x32_bf16 v[104:107], v[136:139], v[190:193], v[104:107]
	v_mfma_f32_16x16x32_bf16 v[92:95], v[128:131], v[198:201], v[92:95]
	v_mfma_f32_16x16x32_bf16 v[88:91], v[136:139], v[198:201], v[88:91]
	v_mfma_f32_16x16x32_bf16 v[76:79], v[128:131], v[206:209], v[76:79]
	v_mfma_f32_16x16x32_bf16 v[72:75], v[136:139], v[206:209], v[72:75]
	v_mfma_f32_16x16x32_bf16 v[124:127], v[132:135], v[186:189], v[124:127]
	v_mfma_f32_16x16x32_bf16 v[120:123], v[140:143], v[186:189], v[120:123]
	v_mfma_f32_16x16x32_bf16 v[108:111], v[132:135], v[194:197], v[108:111]
	v_mfma_f32_16x16x32_bf16 v[104:107], v[140:143], v[194:197], v[104:107]
	v_mfma_f32_16x16x32_bf16 v[92:95], v[132:135], v[202:205], v[92:95]
	v_mfma_f32_16x16x32_bf16 v[88:91], v[140:143], v[202:205], v[88:91]
	v_mfma_f32_16x16x32_bf16 v[76:79], v[132:135], v[210:213], v[76:79]
	v_mfma_f32_16x16x32_bf16 v[72:75], v[140:143], v[210:213], v[72:75]
	s_setprio 0
	s_setprio 1
	v_mfma_f32_16x16x32_bf16 v[116:119], v[154:157], v[178:181], v[116:119]
	v_mfma_f32_16x16x32_bf16 v[112:115], v[166:169], v[178:181], v[112:115]
	v_mfma_f32_16x16x32_bf16 v[100:103], v[154:157], v[190:193], v[100:103]
	v_mfma_f32_16x16x32_bf16 v[96:99], v[166:169], v[190:193], v[96:99]
	v_mfma_f32_16x16x32_bf16 v[84:87], v[154:157], v[198:201], v[84:87]
	v_mfma_f32_16x16x32_bf16 v[80:83], v[166:169], v[198:201], v[80:83]
	v_mfma_f32_16x16x32_bf16 v[68:71], v[154:157], v[206:209], v[68:71]
	v_mfma_f32_16x16x32_bf16 v[64:67], v[166:169], v[206:209], v[64:67]
	v_mfma_f32_16x16x32_bf16 v[116:119], v[158:161], v[186:189], v[116:119]
	v_mfma_f32_16x16x32_bf16 v[112:115], v[170:173], v[186:189], v[112:115]
	v_mfma_f32_16x16x32_bf16 v[100:103], v[158:161], v[194:197], v[100:103]
	v_mfma_f32_16x16x32_bf16 v[96:99], v[170:173], v[194:197], v[96:99]
	v_mfma_f32_16x16x32_bf16 v[84:87], v[158:161], v[202:205], v[84:87]
	v_mfma_f32_16x16x32_bf16 v[80:83], v[170:173], v[202:205], v[80:83]
	v_mfma_f32_16x16x32_bf16 v[68:71], v[158:161], v[210:213], v[68:71]
	v_mfma_f32_16x16x32_bf16 v[64:67], v[170:173], v[210:213], v[64:67]
	s_setprio 0
	s_barrier
	s_add_i32 s54, s72, s12
	v_lshl_add_u64 v[162:163], s[4:5], 0, v[176:177]
	s_mov_b32 m0, s54
	ds_read_b128 v[178:181], v165 offset:16384
	ds_read_b128 v[186:189], v165 offset:17408
	ds_read_b128 v[190:193], v165 offset:18432
	ds_read_b128 v[194:197], v165 offset:19456
	ds_read_b128 v[198:201], v165 offset:20480
	ds_read_b128 v[202:205], v165 offset:21504
	ds_read_b128 v[206:209], v165 offset:22528
	ds_read_b128 v[210:213], v165 offset:23552
	global_load_lds_dwordx4 v176, s[4:5]
	s_add_i32 m0, s54, 0x2000
	s_add_u32 s54, s4, 0xb0000
	v_lshl_add_u64 v[174:175], s[4:5], 0, v[144:145]
	s_addc_u32 s55, s5, 0
	s_add_i32 s72, s73, s12
	global_load_lds_dwordx4 v144, s[4:5]
	s_mov_b32 m0, s72
	v_lshl_add_u64 v[214:215], s[42:43], 0, v[146:147]
	global_load_lds_dwordx4 v176, s[54:55]
	s_add_i32 m0, s72, 0x2000
	s_nop 0
	global_load_lds_dwordx4 v144, s[54:55]
	v_lshl_add_u64 v[182:183], s[42:43], 0, v[148:149]
	s_mov_b32 m0, s20
	s_nop 0
	global_load_lds_dwordx4 v148, s[42:43]
	s_mov_b32 m0, s27
	s_nop 0
	global_load_lds_dwordx4 v146, s[42:43]
	s_waitcnt vmcnt(8)
	s_waitcnt lgkmcnt(0)
	s_barrier
	s_setprio 1
	s_waitcnt lgkmcnt(0)
	v_mfma_f32_16x16x32_bf16 v[60:63], v[128:131], v[178:181], v[60:63]
	v_mfma_f32_16x16x32_bf16 v[56:59], v[136:139], v[178:181], v[56:59]
	v_mfma_f32_16x16x32_bf16 v[44:47], v[128:131], v[190:193], v[44:47]
	v_mfma_f32_16x16x32_bf16 v[40:43], v[136:139], v[190:193], v[40:43]
	v_mfma_f32_16x16x32_bf16 v[28:31], v[128:131], v[198:201], v[28:31]
	v_mfma_f32_16x16x32_bf16 v[24:27], v[136:139], v[198:201], v[24:27]
	v_mfma_f32_16x16x32_bf16 v[12:15], v[128:131], v[206:209], v[12:15]
	v_mfma_f32_16x16x32_bf16 v[8:11], v[136:139], v[206:209], v[8:11]
	v_mfma_f32_16x16x32_bf16 v[60:63], v[132:135], v[186:189], v[60:63]
	v_mfma_f32_16x16x32_bf16 v[56:59], v[140:143], v[186:189], v[56:59]
	v_mfma_f32_16x16x32_bf16 v[44:47], v[132:135], v[194:197], v[44:47]
	v_mfma_f32_16x16x32_bf16 v[40:43], v[140:143], v[194:197], v[40:43]
	v_mfma_f32_16x16x32_bf16 v[28:31], v[132:135], v[202:205], v[28:31]
	v_mfma_f32_16x16x32_bf16 v[24:27], v[140:143], v[202:205], v[24:27]
	v_mfma_f32_16x16x32_bf16 v[12:15], v[132:135], v[210:213], v[12:15]
	v_mfma_f32_16x16x32_bf16 v[8:11], v[140:143], v[210:213], v[8:11]
	s_setprio 0
	s_setprio 1
	v_mfma_f32_16x16x32_bf16 v[52:55], v[154:157], v[178:181], v[52:55]
	v_mfma_f32_16x16x32_bf16 v[48:51], v[166:169], v[178:181], v[48:51]
	v_mfma_f32_16x16x32_bf16 v[36:39], v[154:157], v[190:193], v[36:39]
	v_mfma_f32_16x16x32_bf16 v[32:35], v[166:169], v[190:193], v[32:35]
	v_mfma_f32_16x16x32_bf16 v[20:23], v[154:157], v[198:201], v[20:23]
	v_mfma_f32_16x16x32_bf16 v[16:19], v[166:169], v[198:201], v[16:19]
	v_mfma_f32_16x16x32_bf16 v[4:7], v[154:157], v[206:209], v[4:7]
	v_mfma_f32_16x16x32_bf16 v[0:3], v[166:169], v[206:209], v[0:3]
	v_mfma_f32_16x16x32_bf16 v[52:55], v[158:161], v[186:189], v[52:55]
	v_mfma_f32_16x16x32_bf16 v[48:51], v[170:173], v[186:189], v[48:51]
	v_mfma_f32_16x16x32_bf16 v[36:39], v[158:161], v[194:197], v[36:39]
	v_mfma_f32_16x16x32_bf16 v[32:35], v[170:173], v[194:197], v[32:35]
	v_mfma_f32_16x16x32_bf16 v[20:23], v[158:161], v[202:205], v[20:23]
	v_mfma_f32_16x16x32_bf16 v[16:19], v[170:173], v[202:205], v[16:19]
	v_mfma_f32_16x16x32_bf16 v[4:7], v[158:161], v[210:213], v[4:7]
	v_mfma_f32_16x16x32_bf16 v[0:3], v[170:173], v[210:213], v[0:3]
	s_setprio 0
	s_barrier
	s_add_i32 s54, 0, 0x18000
	s_add_i32 s55, 0, 0x1c000
	v_add_u32_e32 v140, s54, v164
	v_add_u32_e32 v170, s55, v164
	ds_read_b128 v[128:131], v140
	ds_read_b128 v[132:135], v140 offset:1024
	ds_read_b128 v[136:139], v140 offset:2048
	ds_read_b128 v[140:143], v140 offset:3072
	ds_read_b128 v[154:157], v170
	ds_read_b128 v[158:161], v170 offset:1024
	ds_read_b128 v[166:169], v170 offset:2048
	ds_read_b128 v[170:173], v170 offset:3072
	s_add_u32 s42, s42, 0xb0000
	s_addc_u32 s43, s43, 0
	s_mov_b32 m0, s47
	ds_read_b128 v[178:181], v165 offset:32768
	ds_read_b128 v[186:189], v165 offset:33792
	ds_read_b128 v[190:193], v165 offset:34816
	ds_read_b128 v[194:197], v165 offset:35840
	ds_read_b128 v[198:201], v165 offset:36864
	ds_read_b128 v[202:205], v165 offset:37888
	ds_read_b128 v[206:209], v165 offset:38912
	ds_read_b128 v[210:213], v165 offset:39936
	global_load_lds_dwordx4 v148, s[42:43]
	s_mov_b32 m0, s56
	s_nop 0
	global_load_lds_dwordx4 v146, s[42:43]
	s_waitcnt vmcnt(8)
	s_waitcnt lgkmcnt(0)
	s_barrier
	s_setprio 1
	s_waitcnt lgkmcnt(0)
	v_mfma_f32_16x16x32_bf16 v[124:127], v[128:131], v[178:181], v[124:127]
	v_mfma_f32_16x16x32_bf16 v[120:123], v[136:139], v[178:181], v[120:123]
	v_mfma_f32_16x16x32_bf16 v[108:111], v[128:131], v[190:193], v[108:111]
	v_mfma_f32_16x16x32_bf16 v[104:107], v[136:139], v[190:193], v[104:107]
	v_mfma_f32_16x16x32_bf16 v[92:95], v[128:131], v[198:201], v[92:95]
	v_mfma_f32_16x16x32_bf16 v[88:91], v[136:139], v[198:201], v[88:91]
	v_mfma_f32_16x16x32_bf16 v[76:79], v[128:131], v[206:209], v[76:79]
	v_mfma_f32_16x16x32_bf16 v[72:75], v[136:139], v[206:209], v[72:75]
	v_mfma_f32_16x16x32_bf16 v[124:127], v[132:135], v[186:189], v[124:127]
	v_mfma_f32_16x16x32_bf16 v[120:123], v[140:143], v[186:189], v[120:123]
	v_mfma_f32_16x16x32_bf16 v[108:111], v[132:135], v[194:197], v[108:111]
	v_mfma_f32_16x16x32_bf16 v[104:107], v[140:143], v[194:197], v[104:107]
	v_mfma_f32_16x16x32_bf16 v[92:95], v[132:135], v[202:205], v[92:95]
	v_mfma_f32_16x16x32_bf16 v[88:91], v[140:143], v[202:205], v[88:91]
	v_mfma_f32_16x16x32_bf16 v[76:79], v[132:135], v[210:213], v[76:79]
	v_mfma_f32_16x16x32_bf16 v[72:75], v[140:143], v[210:213], v[72:75]
	s_setprio 0
	s_setprio 1
	v_mfma_f32_16x16x32_bf16 v[116:119], v[154:157], v[178:181], v[116:119]
	v_mfma_f32_16x16x32_bf16 v[112:115], v[166:169], v[178:181], v[112:115]
	v_mfma_f32_16x16x32_bf16 v[100:103], v[154:157], v[190:193], v[100:103]
	v_mfma_f32_16x16x32_bf16 v[96:99], v[166:169], v[190:193], v[96:99]
	v_mfma_f32_16x16x32_bf16 v[84:87], v[154:157], v[198:201], v[84:87]
	v_mfma_f32_16x16x32_bf16 v[80:83], v[166:169], v[198:201], v[80:83]
	v_mfma_f32_16x16x32_bf16 v[68:71], v[154:157], v[206:209], v[68:71]
	v_mfma_f32_16x16x32_bf16 v[64:67], v[166:169], v[206:209], v[64:67]
	v_mfma_f32_16x16x32_bf16 v[116:119], v[158:161], v[186:189], v[116:119]
	v_mfma_f32_16x16x32_bf16 v[112:115], v[170:173], v[186:189], v[112:115]
	v_mfma_f32_16x16x32_bf16 v[100:103], v[158:161], v[194:197], v[100:103]
	v_mfma_f32_16x16x32_bf16 v[96:99], v[170:173], v[194:197], v[96:99]
	v_mfma_f32_16x16x32_bf16 v[84:87], v[158:161], v[202:205], v[84:87]
	v_mfma_f32_16x16x32_bf16 v[80:83], v[170:173], v[202:205], v[80:83]
	v_mfma_f32_16x16x32_bf16 v[68:71], v[158:161], v[210:213], v[68:71]
	v_mfma_f32_16x16x32_bf16 v[64:67], v[170:173], v[210:213], v[64:67]
	s_setprio 0
	s_barrier
	s_add_i32 s42, s54, s12
	v_lshl_add_u64 v[162:163], v[162:163], 0, s[82:83]
	s_mov_b32 m0, s42
	ds_read_b128 v[178:181], v165 offset:49152
	ds_read_b128 v[186:189], v165 offset:50176
	ds_read_b128 v[190:193], v165 offset:51200
	ds_read_b128 v[194:197], v165 offset:52224
	ds_read_b128 v[198:201], v165 offset:53248
	ds_read_b128 v[202:205], v165 offset:54272
	ds_read_b128 v[206:209], v165 offset:55296
	ds_read_b128 v[210:213], v165 offset:56320
	global_load_lds_dwordx4 v[162:163], off
	s_add_i32 m0, s42, 0x2000
	s_add_u32 s4, s4, 0xb0080
	v_lshl_add_u64 v[162:163], v[174:175], 0, s[82:83]
	s_addc_u32 s5, s5, 0
	s_add_i32 s42, s55, s12
	global_load_lds_dwordx4 v[162:163], off
	s_mov_b32 m0, s42
	s_nop 0
	global_load_lds_dwordx4 v176, s[4:5]
	s_add_i32 m0, s42, 0x2000
	s_nop 0
	global_load_lds_dwordx4 v144, s[4:5]
	v_lshl_add_u64 v[162:163], v[182:183], 0, s[82:83]
	s_mov_b32 m0, s62
	s_nop 0
	global_load_lds_dwordx4 v[162:163], off
	v_lshl_add_u64 v[162:163], v[214:215], 0, s[82:83]
	s_mov_b32 m0, s63
	s_nop 0
	global_load_lds_dwordx4 v[162:163], off
	s_waitcnt vmcnt(8)
	s_waitcnt lgkmcnt(0)
	s_barrier
	s_setprio 1
	s_waitcnt lgkmcnt(0)
	v_mfma_f32_16x16x32_bf16 v[60:63], v[128:131], v[178:181], v[60:63]
	v_mfma_f32_16x16x32_bf16 v[56:59], v[136:139], v[178:181], v[56:59]
	v_mfma_f32_16x16x32_bf16 v[44:47], v[128:131], v[190:193], v[44:47]
	v_mfma_f32_16x16x32_bf16 v[40:43], v[136:139], v[190:193], v[40:43]
	v_mfma_f32_16x16x32_bf16 v[28:31], v[128:131], v[198:201], v[28:31]
	v_mfma_f32_16x16x32_bf16 v[24:27], v[136:139], v[198:201], v[24:27]
	v_mfma_f32_16x16x32_bf16 v[12:15], v[128:131], v[206:209], v[12:15]
	v_mfma_f32_16x16x32_bf16 v[8:11], v[136:139], v[206:209], v[8:11]
	v_mfma_f32_16x16x32_bf16 v[60:63], v[132:135], v[186:189], v[60:63]
	v_mfma_f32_16x16x32_bf16 v[56:59], v[140:143], v[186:189], v[56:59]
	v_mfma_f32_16x16x32_bf16 v[44:47], v[132:135], v[194:197], v[44:47]
	v_mfma_f32_16x16x32_bf16 v[40:43], v[140:143], v[194:197], v[40:43]
	v_mfma_f32_16x16x32_bf16 v[28:31], v[132:135], v[202:205], v[28:31]
	v_mfma_f32_16x16x32_bf16 v[24:27], v[140:143], v[202:205], v[24:27]
	v_mfma_f32_16x16x32_bf16 v[12:15], v[132:135], v[210:213], v[12:15]
	v_mfma_f32_16x16x32_bf16 v[8:11], v[140:143], v[210:213], v[8:11]
	s_setprio 0
	s_setprio 1
	v_mfma_f32_16x16x32_bf16 v[52:55], v[154:157], v[178:181], v[52:55]
	v_mfma_f32_16x16x32_bf16 v[48:51], v[166:169], v[178:181], v[48:51]
	v_mfma_f32_16x16x32_bf16 v[36:39], v[154:157], v[190:193], v[36:39]
	v_mfma_f32_16x16x32_bf16 v[32:35], v[166:169], v[190:193], v[32:35]
	v_mfma_f32_16x16x32_bf16 v[20:23], v[154:157], v[198:201], v[20:23]
	v_mfma_f32_16x16x32_bf16 v[16:19], v[166:169], v[198:201], v[16:19]
	v_mfma_f32_16x16x32_bf16 v[4:7], v[154:157], v[206:209], v[4:7]
	v_mfma_f32_16x16x32_bf16 v[0:3], v[166:169], v[206:209], v[0:3]
	v_mfma_f32_16x16x32_bf16 v[52:55], v[158:161], v[186:189], v[52:55]
	v_mfma_f32_16x16x32_bf16 v[48:51], v[170:173], v[186:189], v[48:51]
	v_mfma_f32_16x16x32_bf16 v[36:39], v[158:161], v[194:197], v[36:39]
	v_mfma_f32_16x16x32_bf16 v[32:35], v[170:173], v[194:197], v[32:35]
	v_mfma_f32_16x16x32_bf16 v[20:23], v[158:161], v[202:205], v[20:23]
	v_mfma_f32_16x16x32_bf16 v[16:19], v[170:173], v[202:205], v[16:19]
	v_mfma_f32_16x16x32_bf16 v[4:7], v[158:161], v[210:213], v[4:7]
	v_mfma_f32_16x16x32_bf16 v[0:3], v[170:173], v[210:213], v[0:3]
	s_setprio 0
	s_barrier
	s_add_i32 s71, s71, 2
	s_add_u32 s69, s69, 0x100
	s_addc_u32 s70, s70, 0
	s_cmp_gt_u32 s71, 41
	s_mov_b64 s[54:55], s[0:1]
	s_cbranch_scc0 .LBB0_930
	s_and_b64 vcc, exec, s[48:49]
	s_cbranch_vccz .LBB0_933
	s_barrier
